# P5 out-proj epilogue rewritten by hand: residual x loads prefetched 5 chunks deep, pack-then-perm stores (1830 -> ~1130 instr per wave-tile); same math
# baseline (speedup 1.0000x reference)
; __device__ __forceinline__ void load_rm4_f32(const float* base, size_t ld, int c, bool odd, float (&x)[4]) {
; #pragma unroll
;   for (int pr = 0; pr < 2; ++pr) {
;     float2 t = *(const float2*)(base + (size_t)(2 * pr + (odd ? 1 : 0)) * ld + (c - (odd ? 1 : 0)));
;     float r = dpp_swap1(odd ? t.x : t.y);
;     x[2 * pr] = odd ? r : t.x; x[2 * pr + 1] = odd ? t.y : r;
;   }
; }
;   __device__ __forceinline__ void operator()(f32x4 (&acc)[2][2][4][2], int brow, int bcol, int wr, int wc, int fr, int fq) const {
;     u16* x1b = (u16*)(p.ws + OFF_X1B);
;     float* ssq1 = (float*)(p.ws + OFF_SSQ1);
;     int slot = (bcol >> 8) * 4 + wc;
;     const bool odd = fr & 1;
;     const int o1 = odd ? 1 : 0;
;     float2 tc[4][2], tn[4][2];
;     {
;       const float* xb0 = xrow(p, brow + wr * 64 + fq * 4);
; #pragma unroll
;       for (int q = 0; q < 4; ++q)
; #pragma unroll
;         for (int pr = 0; pr < 2; ++pr)
;           tc[q][pr] = *(const float2*)(xb0 + (size_t)(2 * pr + o1) * 1024 + (bcol + (q >> 1) * 128 + wc * 32 + (q & 1) * 16 + fr - o1));
;     }
; #pragma unroll
;     for (int ch = 0; ch < 8; ++ch) {
;       const int ai = ch >> 2, m = ch & 3;
;       int row0 = brow + ai * 128 + wr * 64 + m * 16 + fq * 4;
;       if (ch + 1 < 8) {
;         const float* xbn = xrow(p, brow + ((ch + 1) >> 2) * 128 + wr * 64 + ((ch + 1) & 3) * 16 + fq * 4);
; #pragma unroll
;         for (int q = 0; q < 4; ++q)
; #pragma unroll
;           for (int pr = 0; pr < 2; ++pr)
;             tn[q][pr] = *(const float2*)(xbn + (size_t)(2 * pr + o1) * 1024 + (bcol + (q >> 1) * 128 + wc * 32 + (q & 1) * 16 + fr - o1));
;       }
;       __builtin_amdgcn_sched_barrier(0);
;       float sq[4] = {0.f, 0.f, 0.f, 0.f};
; #pragma unroll
;       for (int q = 0; q < 4; ++q) {
;         const int bj = q >> 1, n = q & 1;
;         int c = bcol + bj * 128 + wc * 32 + n * 16 + fr;
;         float v[4];
; #pragma unroll
;         for (int pr = 0; pr < 2; ++pr) {
;           float2 t = tc[q][pr];
;           float r = dpp_swap1(odd ? t.x : t.y);
;           v[2 * pr] = odd ? r : t.x; v[2 * pr + 1] = odd ? t.y : r;
.LBB0_462:
	v_mbcnt_lo_u32_b32 v130, -1, 0
	v_mbcnt_hi_u32_b32 v130, -1, v130
	s_mov_b32 s3, s2
	s_cmp_lt_i32 s3, s60
	s_cbranch_scc0 .Lmy_eo_sample
	s_lshl_b32 s2, s3, 12
	s_add_u32 s98, s52, s2
	s_addc_u32 s99, s53, 0
	s_branch .Lmy_eo_xdone
.Lmy_eo_sample:
	s_sub_i32 s2, s3, s60
	s_lshl_b32 s2, s2, 12
	s_add_u32 s98, s54, s2
	s_addc_u32 s99, s55, 0
.Lmy_eo_xdone:
	s_lshl_b32 s2, s3, 11
	s_add_u32 s100, s6, s2
	s_addc_u32 s101, s7, 0
	v_and_b32_e32 v131, 15, v130
	v_lshrrev_b32_e32 v132, 2, v130
	v_and_b32_e32 v132, 12, v132
	v_and_b32_e32 v133, 1, v130
	s_lshr_b32 s1, s33, 8
	s_lshl_b32 s1, s1, 6
	s_bfe_u32 s2, s33, 0x20006
	v_add_u32_e32 v128, s1, v132
	v_lshlrev_b32_e32 v137, 6, v128
	v_add_u32_e32 v128, v128, v133
	v_lshlrev_b32_e32 v135, 12, v128
	v_lshlrev_b32_e32 v136, 11, v128
	s_lshl_b32 s1, s2, 5
	s_add_i32 s1, s1, s0
	v_sub_u32_e32 v128, v131, v133
	v_add_u32_e32 v128, s1, v128
	v_lshl_add_u32 v135, v128, 2, v135
	v_lshl_add_u32 v136, v128, 1, v136
	s_ashr_i32 s1, s0, 6
	s_add_i32 s1, s1, s2
	s_lshl_b32 s1, s1, 2
	v_add_u32_e32 v137, s1, v137
	s_lshl_b32 s2, s3, 6
	s_add_u32 s2, s8, s2
	s_addc_u32 s3, s9, 0
	v_mov_b32_e32 v134, 0x05040100
	v_mov_b32_e32 v128, 0x03020706
	v_cmp_eq_u32_e64 s[0:1], 0, v131
	v_cmp_eq_u32_e32 vcc, 1, v133
	s_nop 1
	v_cndmask_b32_e32 v134, v134, v128, vcc
	v_add_u32_e32 v138, 0x0, v135
	v_add_u32_e32 v139, 0x2000, v135
	global_load_dwordx2 v[176:177], v138, s[98:99]
	global_load_dwordx2 v[178:179], v139, s[98:99]
	global_load_dwordx2 v[180:181], v138, s[98:99] offset:64
	global_load_dwordx2 v[182:183], v139, s[98:99] offset:64
	global_load_dwordx2 v[184:185], v138, s[98:99] offset:512
	global_load_dwordx2 v[186:187], v139, s[98:99] offset:512
	global_load_dwordx2 v[188:189], v138, s[98:99] offset:576
	global_load_dwordx2 v[190:191], v139, s[98:99] offset:576
	v_add_u32_e32 v138, 0x10000, v135
	v_add_u32_e32 v139, 0x12000, v135
	global_load_dwordx2 v[192:193], v138, s[98:99]
	global_load_dwordx2 v[194:195], v139, s[98:99]
	global_load_dwordx2 v[196:197], v138, s[98:99] offset:64
	global_load_dwordx2 v[198:199], v139, s[98:99] offset:64
	global_load_dwordx2 v[200:201], v138, s[98:99] offset:512
	global_load_dwordx2 v[202:203], v139, s[98:99] offset:512
	global_load_dwordx2 v[204:205], v138, s[98:99] offset:576
	global_load_dwordx2 v[206:207], v139, s[98:99] offset:576
	v_add_u32_e32 v138, 0x20000, v135
	v_add_u32_e32 v139, 0x22000, v135
	global_load_dwordx2 v[208:209], v138, s[98:99]
	global_load_dwordx2 v[210:211], v139, s[98:99]
	global_load_dwordx2 v[212:213], v138, s[98:99] offset:64
	global_load_dwordx2 v[214:215], v139, s[98:99] offset:64
	global_load_dwordx2 v[216:217], v138, s[98:99] offset:512
	global_load_dwordx2 v[218:219], v139, s[98:99] offset:512
	global_load_dwordx2 v[220:221], v138, s[98:99] offset:576
	global_load_dwordx2 v[222:223], v139, s[98:99] offset:576
	v_add_u32_e32 v138, 0x30000, v135
	v_add_u32_e32 v139, 0x32000, v135
	global_load_dwordx2 v[224:225], v138, s[98:99]
	global_load_dwordx2 v[226:227], v139, s[98:99]
	global_load_dwordx2 v[228:229], v138, s[98:99] offset:64
	global_load_dwordx2 v[230:231], v139, s[98:99] offset:64
	global_load_dwordx2 v[232:233], v138, s[98:99] offset:512
	global_load_dwordx2 v[234:235], v139, s[98:99] offset:512
	global_load_dwordx2 v[236:237], v138, s[98:99] offset:576
	global_load_dwordx2 v[238:239], v139, s[98:99] offset:576
	v_add_u32_e32 v138, 0x80000, v135
	v_add_u32_e32 v139, 0x82000, v135
	global_load_dwordx2 v[240:241], v138, s[98:99]
	global_load_dwordx2 v[242:243], v139, s[98:99]
	global_load_dwordx2 v[244:245], v138, s[98:99] offset:64
	global_load_dwordx2 v[246:247], v139, s[98:99] offset:64
	global_load_dwordx2 v[248:249], v138, s[98:99] offset:512
	global_load_dwordx2 v[250:251], v139, s[98:99] offset:512
	global_load_dwordx2 v[252:253], v138, s[98:99] offset:576
	global_load_dwordx2 v[254:255], v139, s[98:99] offset:576
	s_waitcnt vmcnt(32)
	v_cndmask_b32_e32 v143, v177, v176, vcc
	v_cndmask_b32_e32 v144, v179, v178, vcc
	v_cndmask_b32_e32 v145, v181, v180, vcc
	v_cndmask_b32_e32 v146, v183, v182, vcc
	v_cndmask_b32_e32 v147, v185, v184, vcc
	v_cndmask_b32_e32 v148, v187, v186, vcc
	v_cndmask_b32_e32 v149, v189, v188, vcc
	v_cndmask_b32_e32 v150, v191, v190, vcc
	v_mov_b32_dpp v143, v143 quad_perm:[1,0,3,2] row_mask:0xf bank_mask:0xf bound_ctrl:1
	v_mov_b32_dpp v144, v144 quad_perm:[1,0,3,2] row_mask:0xf bank_mask:0xf bound_ctrl:1
	v_mov_b32_dpp v145, v145 quad_perm:[1,0,3,2] row_mask:0xf bank_mask:0xf bound_ctrl:1
	v_mov_b32_dpp v146, v146 quad_perm:[1,0,3,2] row_mask:0xf bank_mask:0xf bound_ctrl:1
	v_mov_b32_dpp v147, v147 quad_perm:[1,0,3,2] row_mask:0xf bank_mask:0xf bound_ctrl:1
	v_mov_b32_dpp v148, v148 quad_perm:[1,0,3,2] row_mask:0xf bank_mask:0xf bound_ctrl:1
	v_mov_b32_dpp v149, v149 quad_perm:[1,0,3,2] row_mask:0xf bank_mask:0xf bound_ctrl:1
	v_mov_b32_dpp v150, v150 quad_perm:[1,0,3,2] row_mask:0xf bank_mask:0xf bound_ctrl:1
	v_cndmask_b32_e32 v176, v176, v143, vcc
	v_cndmask_b32_e32 v177, v143, v177, vcc
	v_cndmask_b32_e32 v178, v178, v144, vcc
	v_cndmask_b32_e32 v179, v144, v179, vcc
	v_cndmask_b32_e32 v180, v180, v145, vcc
	v_cndmask_b32_e32 v181, v145, v181, vcc
	v_cndmask_b32_e32 v182, v182, v146, vcc
	v_cndmask_b32_e32 v183, v146, v183, vcc
	v_cndmask_b32_e32 v184, v184, v147, vcc
	v_cndmask_b32_e32 v185, v147, v185, vcc
	v_cndmask_b32_e32 v186, v186, v148, vcc
	v_cndmask_b32_e32 v187, v148, v187, vcc
	v_cndmask_b32_e32 v188, v188, v149, vcc
	v_cndmask_b32_e32 v189, v149, v189, vcc
	v_cndmask_b32_e32 v190, v190, v150, vcc
	v_cndmask_b32_e32 v191, v150, v191, vcc
	v_add_f32_e32 v124, v124, v176
; __device__ __forceinline__ float row16_sum(float v) {
;   v += dpp_f<0x128>(v); v += dpp_f<0x124>(v); v += dpp_f<0x122>(v); v += dpp_f<0x121>(v);
;   return v;
; }
;   __device__ __forceinline__ void operator()(f32x4 (&acc)[2][2][4][2], int brow, int bcol, int wr, int wc, int fr, int fq) const {
;     ...
;         for (int pr = 0; pr < 2; ++pr) {
;           float2 t = tc[q][pr];
;           float r = dpp_swap1(odd ? t.x : t.y);
;           v[2 * pr] = odd ? r : t.x; v[2 * pr + 1] = odd ? t.y : r;
;         }
; #pragma unroll
;         for (int j = 0; j < 4; ++j) { v[j] += acc[ai][bj][m][n][j]; sq[j] += v[j] * v[j]; }
;         store_rm4(x1b, 1024, row0, c, v[0], v[1], v[2], v[3], odd);
;       }
; #pragma unroll
;       for (int j = 0; j < 4; ++j) {
;         float t = row16_sum(sq[j]);
;         if (fr == 0) ssq1[(size_t)(row0 + j) * 16 + slot] = t;
;       }
;       __builtin_amdgcn_sched_barrier(0);
; #pragma unroll
;       for (int q = 0; q < 4; ++q) { tc[q][0] = tn[q][0]; tc[q][1] = tn[q][1]; }
;     }
	v_add_f32_e32 v125, v125, v177
	v_add_f32_e32 v126, v126, v178
	v_add_f32_e32 v127, v127, v179
	v_add_f32_e32 v120, v120, v180
	v_add_f32_e32 v121, v121, v181
	v_add_f32_e32 v122, v122, v182
	v_add_f32_e32 v123, v123, v183
	v_add_f32_e32 v116, v116, v184
	v_add_f32_e32 v117, v117, v185
	v_add_f32_e32 v118, v118, v186
	v_add_f32_e32 v119, v119, v187
	v_add_f32_e32 v112, v112, v188
	v_add_f32_e32 v113, v113, v189
	v_add_f32_e32 v114, v114, v190
	v_add_f32_e32 v115, v115, v191
	v_mul_f32_e32 v151, v124, v124
	v_mul_f32_e32 v152, v125, v125
	v_mul_f32_e32 v153, v126, v126
	v_mul_f32_e32 v154, v127, v127
	v_fmac_f32_e32 v151, v120, v120
	v_fmac_f32_e32 v152, v121, v121
	v_fmac_f32_e32 v153, v122, v122
	v_fmac_f32_e32 v154, v123, v123
	v_fmac_f32_e32 v151, v116, v116
	v_fmac_f32_e32 v152, v117, v117
	v_fmac_f32_e32 v153, v118, v118
	v_fmac_f32_e32 v154, v119, v119
	v_fmac_f32_e32 v151, v112, v112
	v_fmac_f32_e32 v152, v113, v113
	v_fmac_f32_e32 v153, v114, v114
	v_fmac_f32_e32 v154, v115, v115
	v_cvt_pk_bf16_f32 v159, v124, v125
	v_cvt_pk_bf16_f32 v161, v126, v127
	v_cvt_pk_bf16_f32 v162, v120, v121
	v_cvt_pk_bf16_f32 v163, v122, v123
	v_cvt_pk_bf16_f32 v164, v116, v117
	v_cvt_pk_bf16_f32 v165, v118, v119
	v_cvt_pk_bf16_f32 v166, v112, v113
	v_cvt_pk_bf16_f32 v167, v114, v115
	v_mov_b32_dpp v168, v159 quad_perm:[1,0,3,2] row_mask:0xf bank_mask:0xf bound_ctrl:1
	v_mov_b32_dpp v169, v161 quad_perm:[1,0,3,2] row_mask:0xf bank_mask:0xf bound_ctrl:1
	v_mov_b32_dpp v170, v162 quad_perm:[1,0,3,2] row_mask:0xf bank_mask:0xf bound_ctrl:1
	v_mov_b32_dpp v171, v163 quad_perm:[1,0,3,2] row_mask:0xf bank_mask:0xf bound_ctrl:1
	v_mov_b32_dpp v172, v164 quad_perm:[1,0,3,2] row_mask:0xf bank_mask:0xf bound_ctrl:1
	v_mov_b32_dpp v173, v165 quad_perm:[1,0,3,2] row_mask:0xf bank_mask:0xf bound_ctrl:1
	v_mov_b32_dpp v174, v166 quad_perm:[1,0,3,2] row_mask:0xf bank_mask:0xf bound_ctrl:1
	v_mov_b32_dpp v175, v167 quad_perm:[1,0,3,2] row_mask:0xf bank_mask:0xf bound_ctrl:1
	v_perm_b32 v159, v168, v159, v134
	v_perm_b32 v161, v169, v161, v134
	v_perm_b32 v162, v170, v162, v134
	v_perm_b32 v163, v171, v163, v134
	v_perm_b32 v164, v172, v164, v134
	v_perm_b32 v165, v173, v165, v134
	v_perm_b32 v166, v174, v166, v134
	v_perm_b32 v167, v175, v167, v134
	v_add_u32_e32 v140, 0x0, v136
	v_add_u32_e32 v141, 0x1000, v136
	global_store_dword v140, v159, s[100:101]
	global_store_dword v141, v161, s[100:101]
	global_store_dword v140, v162, s[100:101] offset:32
	global_store_dword v141, v163, s[100:101] offset:32
	global_store_dword v140, v164, s[100:101] offset:256
	global_store_dword v141, v165, s[100:101] offset:256
	global_store_dword v140, v166, s[100:101] offset:288
	global_store_dword v141, v167, s[100:101] offset:288
	v_add_f32_dpp v151, v151, v151 row_ror:8 row_mask:0xf bank_mask:0xf bound_ctrl:1
	v_add_f32_dpp v152, v152, v152 row_ror:8 row_mask:0xf bank_mask:0xf bound_ctrl:1
	v_add_f32_dpp v153, v153, v153 row_ror:8 row_mask:0xf bank_mask:0xf bound_ctrl:1
	v_add_f32_dpp v154, v154, v154 row_ror:8 row_mask:0xf bank_mask:0xf bound_ctrl:1
	v_add_f32_dpp v151, v151, v151 row_ror:4 row_mask:0xf bank_mask:0xf bound_ctrl:1
	v_add_f32_dpp v152, v152, v152 row_ror:4 row_mask:0xf bank_mask:0xf bound_ctrl:1
	v_add_f32_dpp v153, v153, v153 row_ror:4 row_mask:0xf bank_mask:0xf bound_ctrl:1
	v_add_f32_dpp v154, v154, v154 row_ror:4 row_mask:0xf bank_mask:0xf bound_ctrl:1
	v_add_f32_dpp v151, v151, v151 row_ror:2 row_mask:0xf bank_mask:0xf bound_ctrl:1
	v_add_f32_dpp v152, v152, v152 row_ror:2 row_mask:0xf bank_mask:0xf bound_ctrl:1
	v_add_f32_dpp v153, v153, v153 row_ror:2 row_mask:0xf bank_mask:0xf bound_ctrl:1
	v_add_f32_dpp v154, v154, v154 row_ror:2 row_mask:0xf bank_mask:0xf bound_ctrl:1
	v_mov_b32_dpp v155, v151 row_ror:1 row_mask:0xf bank_mask:0xf bound_ctrl:1
	v_mov_b32_dpp v156, v152 row_ror:1 row_mask:0xf bank_mask:0xf bound_ctrl:1
	v_mov_b32_dpp v157, v153 row_ror:1 row_mask:0xf bank_mask:0xf bound_ctrl:1
	v_mov_b32_dpp v158, v154 row_ror:1 row_mask:0xf bank_mask:0xf bound_ctrl:1
	s_mov_b64 exec, s[0:1]
	v_add_f32_e32 v151, v151, v155
	v_add_f32_e32 v152, v152, v156
	v_add_f32_e32 v153, v153, v157
	v_add_f32_e32 v154, v154, v158
	global_store_dword v137, v151, s[2:3] offset:0
	global_store_dword v137, v152, s[2:3] offset:64
	global_store_dword v137, v153, s[2:3] offset:128
	global_store_dword v137, v154, s[2:3] offset:192
	s_mov_b64 exec, -1
	v_add_u32_e32 v138, 0x90000, v135
	v_add_u32_e32 v139, 0x92000, v135
	global_load_dwordx2 v[176:177], v138, s[98:99]
	global_load_dwordx2 v[178:179], v139, s[98:99]
	global_load_dwordx2 v[180:181], v138, s[98:99] offset:64
	global_load_dwordx2 v[182:183], v139, s[98:99] offset:64
	global_load_dwordx2 v[184:185], v138, s[98:99] offset:512
	global_load_dwordx2 v[186:187], v139, s[98:99] offset:512
	global_load_dwordx2 v[188:189], v138, s[98:99] offset:576
	global_load_dwordx2 v[190:191], v139, s[98:99] offset:576
	s_waitcnt vmcnt(44)
;   __device__ __forceinline__ void operator()(f32x4 (&acc)[2][2][4][2], int brow, int bcol, int wr, int wc, int fr, int fq) const {
;     ...
;     for (int ch = 0; ch < 8; ++ch) {
;       const int ai = ch >> 2, m = ch & 3;
;       int row0 = brow + ai * 128 + wr * 64 + m * 16 + fq * 4;
;       if (ch + 1 < 8) {
;         const float* xbn = xrow(p, brow + ((ch + 1) >> 2) * 128 + wr * 64 + ((ch + 1) & 3) * 16 + fq * 4);
; #pragma unroll
;         for (int q = 0; q < 4; ++q)
; #pragma unroll
;           for (int pr = 0; pr < 2; ++pr)
;             tn[q][pr] = *(const float2*)(xbn + (size_t)(2 * pr + o1) * 1024 + (bcol + (q >> 1) * 128 + wc * 32 + (q & 1) * 16 + fr - o1));
;       }
;       __builtin_amdgcn_sched_barrier(0);
;       float sq[4] = {0.f, 0.f, 0.f, 0.f};
; #pragma unroll
;       for (int q = 0; q < 4; ++q) {
;         const int bj = q >> 1, n = q & 1;
;         int c = bcol + bj * 128 + wc * 32 + n * 16 + fr;
;         float v[4];
; #pragma unroll
;         for (int pr = 0; pr < 2; ++pr) {
;           float2 t = tc[q][pr];
;           float r = dpp_swap1(odd ? t.x : t.y);
;           v[2 * pr] = odd ? r : t.x; v[2 * pr + 1] = odd ? t.y : r;
;         }
; #pragma unroll
;         for (int j = 0; j < 4; ++j) { v[j] += acc[ai][bj][m][n][j]; sq[j] += v[j] * v[j]; }
;         store_rm4(x1b, 1024, row0, c, v[0], v[1], v[2], v[3], odd);
;       }
; #pragma unroll
;       for (int j = 0; j < 4; ++j) {
;         float t = row16_sum(sq[j]);
;         if (fr == 0) ssq1[(size_t)(row0 + j) * 16 + slot] = t;
;       }
;       __builtin_amdgcn_sched_barrier(0);
; #pragma unroll
;       for (int q = 0; q < 4; ++q) { tc[q][0] = tn[q][0]; tc[q][1] = tn[q][1]; }
;     }
	v_cndmask_b32_e32 v143, v193, v192, vcc
	v_cndmask_b32_e32 v144, v195, v194, vcc
	v_cndmask_b32_e32 v145, v197, v196, vcc
	v_cndmask_b32_e32 v146, v199, v198, vcc
	v_cndmask_b32_e32 v147, v201, v200, vcc
	v_cndmask_b32_e32 v148, v203, v202, vcc
	v_cndmask_b32_e32 v149, v205, v204, vcc
	v_cndmask_b32_e32 v150, v207, v206, vcc
	v_mov_b32_dpp v143, v143 quad_perm:[1,0,3,2] row_mask:0xf bank_mask:0xf bound_ctrl:1
	v_mov_b32_dpp v144, v144 quad_perm:[1,0,3,2] row_mask:0xf bank_mask:0xf bound_ctrl:1
	v_mov_b32_dpp v145, v145 quad_perm:[1,0,3,2] row_mask:0xf bank_mask:0xf bound_ctrl:1
	v_mov_b32_dpp v146, v146 quad_perm:[1,0,3,2] row_mask:0xf bank_mask:0xf bound_ctrl:1
	v_mov_b32_dpp v147, v147 quad_perm:[1,0,3,2] row_mask:0xf bank_mask:0xf bound_ctrl:1
	v_mov_b32_dpp v148, v148 quad_perm:[1,0,3,2] row_mask:0xf bank_mask:0xf bound_ctrl:1
	v_mov_b32_dpp v149, v149 quad_perm:[1,0,3,2] row_mask:0xf bank_mask:0xf bound_ctrl:1
	v_mov_b32_dpp v150, v150 quad_perm:[1,0,3,2] row_mask:0xf bank_mask:0xf bound_ctrl:1
	v_cndmask_b32_e32 v192, v192, v143, vcc
	v_cndmask_b32_e32 v193, v143, v193, vcc
	v_cndmask_b32_e32 v194, v194, v144, vcc
	v_cndmask_b32_e32 v195, v144, v195, vcc
	v_cndmask_b32_e32 v196, v196, v145, vcc
	v_cndmask_b32_e32 v197, v145, v197, vcc
	v_cndmask_b32_e32 v198, v198, v146, vcc
	v_cndmask_b32_e32 v199, v146, v199, vcc
	v_cndmask_b32_e32 v200, v200, v147, vcc
	v_cndmask_b32_e32 v201, v147, v201, vcc
	v_cndmask_b32_e32 v202, v202, v148, vcc
	v_cndmask_b32_e32 v203, v148, v203, vcc
	v_cndmask_b32_e32 v204, v204, v149, vcc
	v_cndmask_b32_e32 v205, v149, v205, vcc
	v_cndmask_b32_e32 v206, v206, v150, vcc
	v_cndmask_b32_e32 v207, v150, v207, vcc
	v_add_f32_e32 v108, v108, v192
	v_add_f32_e32 v109, v109, v193
	v_add_f32_e32 v110, v110, v194
	v_add_f32_e32 v111, v111, v195
	v_add_f32_e32 v104, v104, v196
	v_add_f32_e32 v105, v105, v197
	v_add_f32_e32 v106, v106, v198
	v_add_f32_e32 v107, v107, v199
	v_add_f32_e32 v100, v100, v200
	v_add_f32_e32 v101, v101, v201
	v_add_f32_e32 v102, v102, v202
	v_add_f32_e32 v103, v103, v203
	v_add_f32_e32 v96, v96, v204
	v_add_f32_e32 v97, v97, v205
	v_add_f32_e32 v98, v98, v206
	v_add_f32_e32 v99, v99, v207
	v_mul_f32_e32 v151, v108, v108
	v_mul_f32_e32 v152, v109, v109
	v_mul_f32_e32 v153, v110, v110
	v_mul_f32_e32 v154, v111, v111
	v_fmac_f32_e32 v151, v104, v104
	v_fmac_f32_e32 v152, v105, v105
	v_fmac_f32_e32 v153, v106, v106
	v_fmac_f32_e32 v154, v107, v107
	v_fmac_f32_e32 v151, v100, v100
	v_fmac_f32_e32 v152, v101, v101
	v_fmac_f32_e32 v153, v102, v102
	v_fmac_f32_e32 v154, v103, v103
	v_fmac_f32_e32 v151, v96, v96
	v_fmac_f32_e32 v152, v97, v97
	v_fmac_f32_e32 v153, v98, v98
	v_fmac_f32_e32 v154, v99, v99
	v_cvt_pk_bf16_f32 v159, v108, v109
	v_cvt_pk_bf16_f32 v161, v110, v111
	v_cvt_pk_bf16_f32 v162, v104, v105
	v_cvt_pk_bf16_f32 v163, v106, v107
	v_cvt_pk_bf16_f32 v164, v100, v101
	v_cvt_pk_bf16_f32 v165, v102, v103
	v_cvt_pk_bf16_f32 v166, v96, v97
	v_cvt_pk_bf16_f32 v167, v98, v99
	v_mov_b32_dpp v168, v159 quad_perm:[1,0,3,2] row_mask:0xf bank_mask:0xf bound_ctrl:1
	v_mov_b32_dpp v169, v161 quad_perm:[1,0,3,2] row_mask:0xf bank_mask:0xf bound_ctrl:1
	v_mov_b32_dpp v170, v162 quad_perm:[1,0,3,2] row_mask:0xf bank_mask:0xf bound_ctrl:1
	v_mov_b32_dpp v171, v163 quad_perm:[1,0,3,2] row_mask:0xf bank_mask:0xf bound_ctrl:1
	v_mov_b32_dpp v172, v164 quad_perm:[1,0,3,2] row_mask:0xf bank_mask:0xf bound_ctrl:1
	v_mov_b32_dpp v173, v165 quad_perm:[1,0,3,2] row_mask:0xf bank_mask:0xf bound_ctrl:1
	v_mov_b32_dpp v174, v166 quad_perm:[1,0,3,2] row_mask:0xf bank_mask:0xf bound_ctrl:1
	v_mov_b32_dpp v175, v167 quad_perm:[1,0,3,2] row_mask:0xf bank_mask:0xf bound_ctrl:1
	v_perm_b32 v159, v168, v159, v134
	v_perm_b32 v161, v169, v161, v134
	v_perm_b32 v162, v170, v162, v134
	v_perm_b32 v163, v171, v163, v134
	v_perm_b32 v164, v172, v164, v134
	v_perm_b32 v165, v173, v165, v134
	v_perm_b32 v166, v174, v166, v134
	v_perm_b32 v167, v175, v167, v134
	v_add_u32_e32 v140, 0x8000, v136
	v_add_u32_e32 v141, 0x9000, v136
	global_store_dword v140, v159, s[100:101]
	global_store_dword v141, v161, s[100:101]
	global_store_dword v140, v162, s[100:101] offset:32
	global_store_dword v141, v163, s[100:101] offset:32
	global_store_dword v140, v164, s[100:101] offset:256
	global_store_dword v141, v165, s[100:101] offset:256
	global_store_dword v140, v166, s[100:101] offset:288
	global_store_dword v141, v167, s[100:101] offset:288
	v_add_f32_dpp v151, v151, v151 row_ror:8 row_mask:0xf bank_mask:0xf bound_ctrl:1
	v_add_f32_dpp v152, v152, v152 row_ror:8 row_mask:0xf bank_mask:0xf bound_ctrl:1
	v_add_f32_dpp v153, v153, v153 row_ror:8 row_mask:0xf bank_mask:0xf bound_ctrl:1
	v_add_f32_dpp v154, v154, v154 row_ror:8 row_mask:0xf bank_mask:0xf bound_ctrl:1
	v_add_f32_dpp v151, v151, v151 row_ror:4 row_mask:0xf bank_mask:0xf bound_ctrl:1
	v_add_f32_dpp v152, v152, v152 row_ror:4 row_mask:0xf bank_mask:0xf bound_ctrl:1
	v_add_f32_dpp v153, v153, v153 row_ror:4 row_mask:0xf bank_mask:0xf bound_ctrl:1
	v_add_f32_dpp v154, v154, v154 row_ror:4 row_mask:0xf bank_mask:0xf bound_ctrl:1
	v_add_f32_dpp v151, v151, v151 row_ror:2 row_mask:0xf bank_mask:0xf bound_ctrl:1
	v_add_f32_dpp v152, v152, v152 row_ror:2 row_mask:0xf bank_mask:0xf bound_ctrl:1
	v_add_f32_dpp v153, v153, v153 row_ror:2 row_mask:0xf bank_mask:0xf bound_ctrl:1
	v_add_f32_dpp v154, v154, v154 row_ror:2 row_mask:0xf bank_mask:0xf bound_ctrl:1
	v_mov_b32_dpp v155, v151 row_ror:1 row_mask:0xf bank_mask:0xf bound_ctrl:1
	v_mov_b32_dpp v156, v152 row_ror:1 row_mask:0xf bank_mask:0xf bound_ctrl:1
	v_mov_b32_dpp v157, v153 row_ror:1 row_mask:0xf bank_mask:0xf bound_ctrl:1
	v_mov_b32_dpp v158, v154 row_ror:1 row_mask:0xf bank_mask:0xf bound_ctrl:1
	s_mov_b64 exec, s[0:1]
	v_add_f32_e32 v151, v151, v155
	v_add_f32_e32 v152, v152, v156
	v_add_f32_e32 v153, v153, v157
	v_add_f32_e32 v154, v154, v158
	global_store_dword v137, v151, s[2:3] offset:1024
	global_store_dword v137, v152, s[2:3] offset:1088
	global_store_dword v137, v153, s[2:3] offset:1152
	global_store_dword v137, v154, s[2:3] offset:1216
	s_mov_b64 exec, -1
	v_add_u32_e32 v138, 0xa0000, v135
	v_add_u32_e32 v139, 0xa2000, v135
	global_load_dwordx2 v[192:193], v138, s[98:99]
	global_load_dwordx2 v[194:195], v139, s[98:99]
	global_load_dwordx2 v[196:197], v138, s[98:99] offset:64
	global_load_dwordx2 v[198:199], v139, s[98:99] offset:64
	global_load_dwordx2 v[200:201], v138, s[98:99] offset:512
	global_load_dwordx2 v[202:203], v139, s[98:99] offset:512
	global_load_dwordx2 v[204:205], v138, s[98:99] offset:576
	global_load_dwordx2 v[206:207], v139, s[98:99] offset:576
	s_waitcnt vmcnt(56)
;   __device__ __forceinline__ void operator()(f32x4 (&acc)[2][2][4][2], int brow, int bcol, int wr, int wc, int fr, int fq) const {
;     ...
;     for (int ch = 0; ch < 8; ++ch) {
;       const int ai = ch >> 2, m = ch & 3;
;       int row0 = brow + ai * 128 + wr * 64 + m * 16 + fq * 4;
;       if (ch + 1 < 8) {
;         const float* xbn = xrow(p, brow + ((ch + 1) >> 2) * 128 + wr * 64 + ((ch + 1) & 3) * 16 + fq * 4);
; #pragma unroll
;         for (int q = 0; q < 4; ++q)
; #pragma unroll
;           for (int pr = 0; pr < 2; ++pr)
;             tn[q][pr] = *(const float2*)(xbn + (size_t)(2 * pr + o1) * 1024 + (bcol + (q >> 1) * 128 + wc * 32 + (q & 1) * 16 + fr - o1));
;       }
;       __builtin_amdgcn_sched_barrier(0);
;       float sq[4] = {0.f, 0.f, 0.f, 0.f};
; #pragma unroll
;       for (int q = 0; q < 4; ++q) {
;         const int bj = q >> 1, n = q & 1;
;         int c = bcol + bj * 128 + wc * 32 + n * 16 + fr;
;         float v[4];
; #pragma unroll
;         for (int pr = 0; pr < 2; ++pr) {
;           float2 t = tc[q][pr];
;           float r = dpp_swap1(odd ? t.x : t.y);
;           v[2 * pr] = odd ? r : t.x; v[2 * pr + 1] = odd ? t.y : r;
;         }
; #pragma unroll
;         for (int j = 0; j < 4; ++j) { v[j] += acc[ai][bj][m][n][j]; sq[j] += v[j] * v[j]; }
;         store_rm4(x1b, 1024, row0, c, v[0], v[1], v[2], v[3], odd);
;       }
; #pragma unroll
;       for (int j = 0; j < 4; ++j) {
;         float t = row16_sum(sq[j]);
;         if (fr == 0) ssq1[(size_t)(row0 + j) * 16 + slot] = t;
;       }
;       __builtin_amdgcn_sched_barrier(0);
; #pragma unroll
;       for (int q = 0; q < 4; ++q) { tc[q][0] = tn[q][0]; tc[q][1] = tn[q][1]; }
;     }
	v_cndmask_b32_e32 v143, v209, v208, vcc
	v_cndmask_b32_e32 v144, v211, v210, vcc
	v_cndmask_b32_e32 v145, v213, v212, vcc
	v_cndmask_b32_e32 v146, v215, v214, vcc
	v_cndmask_b32_e32 v147, v217, v216, vcc
	v_cndmask_b32_e32 v148, v219, v218, vcc
	v_cndmask_b32_e32 v149, v221, v220, vcc
	v_cndmask_b32_e32 v150, v223, v222, vcc
	v_mov_b32_dpp v143, v143 quad_perm:[1,0,3,2] row_mask:0xf bank_mask:0xf bound_ctrl:1
	v_mov_b32_dpp v144, v144 quad_perm:[1,0,3,2] row_mask:0xf bank_mask:0xf bound_ctrl:1
	v_mov_b32_dpp v145, v145 quad_perm:[1,0,3,2] row_mask:0xf bank_mask:0xf bound_ctrl:1
	v_mov_b32_dpp v146, v146 quad_perm:[1,0,3,2] row_mask:0xf bank_mask:0xf bound_ctrl:1
	v_mov_b32_dpp v147, v147 quad_perm:[1,0,3,2] row_mask:0xf bank_mask:0xf bound_ctrl:1
	v_mov_b32_dpp v148, v148 quad_perm:[1,0,3,2] row_mask:0xf bank_mask:0xf bound_ctrl:1
	v_mov_b32_dpp v149, v149 quad_perm:[1,0,3,2] row_mask:0xf bank_mask:0xf bound_ctrl:1
	v_mov_b32_dpp v150, v150 quad_perm:[1,0,3,2] row_mask:0xf bank_mask:0xf bound_ctrl:1
	v_cndmask_b32_e32 v208, v208, v143, vcc
	v_cndmask_b32_e32 v209, v143, v209, vcc
	v_cndmask_b32_e32 v210, v210, v144, vcc
	v_cndmask_b32_e32 v211, v144, v211, vcc
	v_cndmask_b32_e32 v212, v212, v145, vcc
	v_cndmask_b32_e32 v213, v145, v213, vcc
	v_cndmask_b32_e32 v214, v214, v146, vcc
	v_cndmask_b32_e32 v215, v146, v215, vcc
	v_cndmask_b32_e32 v216, v216, v147, vcc
	v_cndmask_b32_e32 v217, v147, v217, vcc
	v_cndmask_b32_e32 v218, v218, v148, vcc
	v_cndmask_b32_e32 v219, v148, v219, vcc
	v_cndmask_b32_e32 v220, v220, v149, vcc
	v_cndmask_b32_e32 v221, v149, v221, vcc
	v_cndmask_b32_e32 v222, v222, v150, vcc
	v_cndmask_b32_e32 v223, v150, v223, vcc
	v_add_f32_e32 v92, v92, v208
	v_add_f32_e32 v93, v93, v209
	v_add_f32_e32 v94, v94, v210
	v_add_f32_e32 v95, v95, v211
	v_add_f32_e32 v88, v88, v212
	v_add_f32_e32 v89, v89, v213
	v_add_f32_e32 v90, v90, v214
	v_add_f32_e32 v91, v91, v215
	v_add_f32_e32 v84, v84, v216
	v_add_f32_e32 v85, v85, v217
	v_add_f32_e32 v86, v86, v218
	v_add_f32_e32 v87, v87, v219
	v_add_f32_e32 v80, v80, v220
	v_add_f32_e32 v81, v81, v221
	v_add_f32_e32 v82, v82, v222
	v_add_f32_e32 v83, v83, v223
	v_mul_f32_e32 v151, v92, v92
	v_mul_f32_e32 v152, v93, v93
	v_mul_f32_e32 v153, v94, v94
	v_mul_f32_e32 v154, v95, v95
	v_fmac_f32_e32 v151, v88, v88
	v_fmac_f32_e32 v152, v89, v89
	v_fmac_f32_e32 v153, v90, v90
	v_fmac_f32_e32 v154, v91, v91
	v_fmac_f32_e32 v151, v84, v84
	v_fmac_f32_e32 v152, v85, v85
	v_fmac_f32_e32 v153, v86, v86
	v_fmac_f32_e32 v154, v87, v87
	v_fmac_f32_e32 v151, v80, v80
	v_fmac_f32_e32 v152, v81, v81
	v_fmac_f32_e32 v153, v82, v82
	v_fmac_f32_e32 v154, v83, v83
	v_cvt_pk_bf16_f32 v159, v92, v93
	v_cvt_pk_bf16_f32 v161, v94, v95
	v_cvt_pk_bf16_f32 v162, v88, v89
	v_cvt_pk_bf16_f32 v163, v90, v91
	v_cvt_pk_bf16_f32 v164, v84, v85
	v_cvt_pk_bf16_f32 v165, v86, v87
	v_cvt_pk_bf16_f32 v166, v80, v81
	v_cvt_pk_bf16_f32 v167, v82, v83
	v_mov_b32_dpp v168, v159 quad_perm:[1,0,3,2] row_mask:0xf bank_mask:0xf bound_ctrl:1
	v_mov_b32_dpp v169, v161 quad_perm:[1,0,3,2] row_mask:0xf bank_mask:0xf bound_ctrl:1
	v_mov_b32_dpp v170, v162 quad_perm:[1,0,3,2] row_mask:0xf bank_mask:0xf bound_ctrl:1
	v_mov_b32_dpp v171, v163 quad_perm:[1,0,3,2] row_mask:0xf bank_mask:0xf bound_ctrl:1
	v_mov_b32_dpp v172, v164 quad_perm:[1,0,3,2] row_mask:0xf bank_mask:0xf bound_ctrl:1
	v_mov_b32_dpp v173, v165 quad_perm:[1,0,3,2] row_mask:0xf bank_mask:0xf bound_ctrl:1
	v_mov_b32_dpp v174, v166 quad_perm:[1,0,3,2] row_mask:0xf bank_mask:0xf bound_ctrl:1
	v_mov_b32_dpp v175, v167 quad_perm:[1,0,3,2] row_mask:0xf bank_mask:0xf bound_ctrl:1
	v_perm_b32 v159, v168, v159, v134
	v_perm_b32 v161, v169, v161, v134
	v_perm_b32 v162, v170, v162, v134
	v_perm_b32 v163, v171, v163, v134
	v_perm_b32 v164, v172, v164, v134
	v_perm_b32 v165, v173, v165, v134
	v_perm_b32 v166, v174, v166, v134
	v_perm_b32 v167, v175, v167, v134
	v_add_u32_e32 v140, 0x10000, v136
	v_add_u32_e32 v141, 0x11000, v136
	global_store_dword v140, v159, s[100:101]
	global_store_dword v141, v161, s[100:101]
	global_store_dword v140, v162, s[100:101] offset:32
	global_store_dword v141, v163, s[100:101] offset:32
	global_store_dword v140, v164, s[100:101] offset:256
	global_store_dword v141, v165, s[100:101] offset:256
	global_store_dword v140, v166, s[100:101] offset:288
	global_store_dword v141, v167, s[100:101] offset:288
	v_add_f32_dpp v151, v151, v151 row_ror:8 row_mask:0xf bank_mask:0xf bound_ctrl:1
	v_add_f32_dpp v152, v152, v152 row_ror:8 row_mask:0xf bank_mask:0xf bound_ctrl:1
	v_add_f32_dpp v153, v153, v153 row_ror:8 row_mask:0xf bank_mask:0xf bound_ctrl:1
	v_add_f32_dpp v154, v154, v154 row_ror:8 row_mask:0xf bank_mask:0xf bound_ctrl:1
	v_add_f32_dpp v151, v151, v151 row_ror:4 row_mask:0xf bank_mask:0xf bound_ctrl:1
	v_add_f32_dpp v152, v152, v152 row_ror:4 row_mask:0xf bank_mask:0xf bound_ctrl:1
	v_add_f32_dpp v153, v153, v153 row_ror:4 row_mask:0xf bank_mask:0xf bound_ctrl:1
	v_add_f32_dpp v154, v154, v154 row_ror:4 row_mask:0xf bank_mask:0xf bound_ctrl:1
	v_add_f32_dpp v151, v151, v151 row_ror:2 row_mask:0xf bank_mask:0xf bound_ctrl:1
	v_add_f32_dpp v152, v152, v152 row_ror:2 row_mask:0xf bank_mask:0xf bound_ctrl:1
	v_add_f32_dpp v153, v153, v153 row_ror:2 row_mask:0xf bank_mask:0xf bound_ctrl:1
	v_add_f32_dpp v154, v154, v154 row_ror:2 row_mask:0xf bank_mask:0xf bound_ctrl:1
	v_mov_b32_dpp v155, v151 row_ror:1 row_mask:0xf bank_mask:0xf bound_ctrl:1
	v_mov_b32_dpp v156, v152 row_ror:1 row_mask:0xf bank_mask:0xf bound_ctrl:1
	v_mov_b32_dpp v157, v153 row_ror:1 row_mask:0xf bank_mask:0xf bound_ctrl:1
	v_mov_b32_dpp v158, v154 row_ror:1 row_mask:0xf bank_mask:0xf bound_ctrl:1
	s_mov_b64 exec, s[0:1]
	v_add_f32_e32 v151, v151, v155
	v_add_f32_e32 v152, v152, v156
	v_add_f32_e32 v153, v153, v157
	v_add_f32_e32 v154, v154, v158
	global_store_dword v137, v151, s[2:3] offset:2048
	global_store_dword v137, v152, s[2:3] offset:2112
	global_store_dword v137, v153, s[2:3] offset:2176
	global_store_dword v137, v154, s[2:3] offset:2240
	s_mov_b64 exec, -1
	v_add_u32_e32 v138, 0xb0000, v135
	v_add_u32_e32 v139, 0xb2000, v135
	global_load_dwordx2 v[208:209], v138, s[98:99]
	global_load_dwordx2 v[210:211], v139, s[98:99]
	global_load_dwordx2 v[212:213], v138, s[98:99] offset:64
	global_load_dwordx2 v[214:215], v139, s[98:99] offset:64
	global_load_dwordx2 v[216:217], v138, s[98:99] offset:512
	global_load_dwordx2 v[218:219], v139, s[98:99] offset:512
	global_load_dwordx2 v[220:221], v138, s[98:99] offset:576
	global_load_dwordx2 v[222:223], v139, s[98:99] offset:576
	s_waitcnt vmcnt(63)
;   __device__ __forceinline__ void operator()(f32x4 (&acc)[2][2][4][2], int brow, int bcol, int wr, int wc, int fr, int fq) const {
;     ...
;     for (int ch = 0; ch < 8; ++ch) {
;       const int ai = ch >> 2, m = ch & 3;
;       int row0 = brow + ai * 128 + wr * 64 + m * 16 + fq * 4;
;       if (ch + 1 < 8) {
;         const float* xbn = xrow(p, brow + ((ch + 1) >> 2) * 128 + wr * 64 + ((ch + 1) & 3) * 16 + fq * 4);
; #pragma unroll
;         for (int q = 0; q < 4; ++q)
; #pragma unroll
;           for (int pr = 0; pr < 2; ++pr)
;             tn[q][pr] = *(const float2*)(xbn + (size_t)(2 * pr + o1) * 1024 + (bcol + (q >> 1) * 128 + wc * 32 + (q & 1) * 16 + fr - o1));
;       }
;       __builtin_amdgcn_sched_barrier(0);
;       float sq[4] = {0.f, 0.f, 0.f, 0.f};
; #pragma unroll
;       for (int q = 0; q < 4; ++q) {
;         const int bj = q >> 1, n = q & 1;
;         int c = bcol + bj * 128 + wc * 32 + n * 16 + fr;
;         float v[4];
; #pragma unroll
;         for (int pr = 0; pr < 2; ++pr) {
;           float2 t = tc[q][pr];
;           float r = dpp_swap1(odd ? t.x : t.y);
;           v[2 * pr] = odd ? r : t.x; v[2 * pr + 1] = odd ? t.y : r;
;         }
; #pragma unroll
;         for (int j = 0; j < 4; ++j) { v[j] += acc[ai][bj][m][n][j]; sq[j] += v[j] * v[j]; }
;         store_rm4(x1b, 1024, row0, c, v[0], v[1], v[2], v[3], odd);
;       }
; #pragma unroll
;       for (int j = 0; j < 4; ++j) {
;         float t = row16_sum(sq[j]);
;         if (fr == 0) ssq1[(size_t)(row0 + j) * 16 + slot] = t;
;       }
;       __builtin_amdgcn_sched_barrier(0);
; #pragma unroll
;       for (int q = 0; q < 4; ++q) { tc[q][0] = tn[q][0]; tc[q][1] = tn[q][1]; }
;     }
	v_cndmask_b32_e32 v143, v225, v224, vcc
	v_cndmask_b32_e32 v144, v227, v226, vcc
	v_cndmask_b32_e32 v145, v229, v228, vcc
	v_cndmask_b32_e32 v146, v231, v230, vcc
	v_cndmask_b32_e32 v147, v233, v232, vcc
	v_cndmask_b32_e32 v148, v235, v234, vcc
	v_cndmask_b32_e32 v149, v237, v236, vcc
	v_cndmask_b32_e32 v150, v239, v238, vcc
	v_mov_b32_dpp v143, v143 quad_perm:[1,0,3,2] row_mask:0xf bank_mask:0xf bound_ctrl:1
	v_mov_b32_dpp v144, v144 quad_perm:[1,0,3,2] row_mask:0xf bank_mask:0xf bound_ctrl:1
	v_mov_b32_dpp v145, v145 quad_perm:[1,0,3,2] row_mask:0xf bank_mask:0xf bound_ctrl:1
	v_mov_b32_dpp v146, v146 quad_perm:[1,0,3,2] row_mask:0xf bank_mask:0xf bound_ctrl:1
	v_mov_b32_dpp v147, v147 quad_perm:[1,0,3,2] row_mask:0xf bank_mask:0xf bound_ctrl:1
	v_mov_b32_dpp v148, v148 quad_perm:[1,0,3,2] row_mask:0xf bank_mask:0xf bound_ctrl:1
	v_mov_b32_dpp v149, v149 quad_perm:[1,0,3,2] row_mask:0xf bank_mask:0xf bound_ctrl:1
	v_mov_b32_dpp v150, v150 quad_perm:[1,0,3,2] row_mask:0xf bank_mask:0xf bound_ctrl:1
	v_cndmask_b32_e32 v224, v224, v143, vcc
	v_cndmask_b32_e32 v225, v143, v225, vcc
	v_cndmask_b32_e32 v226, v226, v144, vcc
	v_cndmask_b32_e32 v227, v144, v227, vcc
	v_cndmask_b32_e32 v228, v228, v145, vcc
	v_cndmask_b32_e32 v229, v145, v229, vcc
	v_cndmask_b32_e32 v230, v230, v146, vcc
	v_cndmask_b32_e32 v231, v146, v231, vcc
	v_cndmask_b32_e32 v232, v232, v147, vcc
	v_cndmask_b32_e32 v233, v147, v233, vcc
	v_cndmask_b32_e32 v234, v234, v148, vcc
	v_cndmask_b32_e32 v235, v148, v235, vcc
	v_cndmask_b32_e32 v236, v236, v149, vcc
	v_cndmask_b32_e32 v237, v149, v237, vcc
	v_cndmask_b32_e32 v238, v238, v150, vcc
	v_cndmask_b32_e32 v239, v150, v239, vcc
	v_add_f32_e32 v76, v76, v224
	v_add_f32_e32 v77, v77, v225
	v_add_f32_e32 v78, v78, v226
	v_add_f32_e32 v79, v79, v227
	v_add_f32_e32 v72, v72, v228
	v_add_f32_e32 v73, v73, v229
	v_add_f32_e32 v74, v74, v230
	v_add_f32_e32 v75, v75, v231
	v_add_f32_e32 v68, v68, v232
	v_add_f32_e32 v69, v69, v233
	v_add_f32_e32 v70, v70, v234
	v_add_f32_e32 v71, v71, v235
	v_add_f32_e32 v64, v64, v236
	v_add_f32_e32 v65, v65, v237
	v_add_f32_e32 v66, v66, v238
	v_add_f32_e32 v67, v67, v239
	v_mul_f32_e32 v151, v76, v76
	v_mul_f32_e32 v152, v77, v77
	v_mul_f32_e32 v153, v78, v78
	v_mul_f32_e32 v154, v79, v79
	v_fmac_f32_e32 v151, v72, v72
	v_fmac_f32_e32 v152, v73, v73
	v_fmac_f32_e32 v153, v74, v74
	v_fmac_f32_e32 v154, v75, v75
	v_fmac_f32_e32 v151, v68, v68
	v_fmac_f32_e32 v152, v69, v69
	v_fmac_f32_e32 v153, v70, v70
	v_fmac_f32_e32 v154, v71, v71
	v_fmac_f32_e32 v151, v64, v64
	v_fmac_f32_e32 v152, v65, v65
	v_fmac_f32_e32 v153, v66, v66
	v_fmac_f32_e32 v154, v67, v67
	v_cvt_pk_bf16_f32 v159, v76, v77
	v_cvt_pk_bf16_f32 v161, v78, v79
	v_cvt_pk_bf16_f32 v162, v72, v73
	v_cvt_pk_bf16_f32 v163, v74, v75
	v_cvt_pk_bf16_f32 v164, v68, v69
	v_cvt_pk_bf16_f32 v165, v70, v71
	v_cvt_pk_bf16_f32 v166, v64, v65
	v_cvt_pk_bf16_f32 v167, v66, v67
	v_mov_b32_dpp v168, v159 quad_perm:[1,0,3,2] row_mask:0xf bank_mask:0xf bound_ctrl:1
	v_mov_b32_dpp v169, v161 quad_perm:[1,0,3,2] row_mask:0xf bank_mask:0xf bound_ctrl:1
	v_mov_b32_dpp v170, v162 quad_perm:[1,0,3,2] row_mask:0xf bank_mask:0xf bound_ctrl:1
	v_mov_b32_dpp v171, v163 quad_perm:[1,0,3,2] row_mask:0xf bank_mask:0xf bound_ctrl:1
	v_mov_b32_dpp v172, v164 quad_perm:[1,0,3,2] row_mask:0xf bank_mask:0xf bound_ctrl:1
	v_mov_b32_dpp v173, v165 quad_perm:[1,0,3,2] row_mask:0xf bank_mask:0xf bound_ctrl:1
	v_mov_b32_dpp v174, v166 quad_perm:[1,0,3,2] row_mask:0xf bank_mask:0xf bound_ctrl:1
	v_mov_b32_dpp v175, v167 quad_perm:[1,0,3,2] row_mask:0xf bank_mask:0xf bound_ctrl:1
	v_perm_b32 v159, v168, v159, v134
	v_perm_b32 v161, v169, v161, v134
	v_perm_b32 v162, v170, v162, v134
	v_perm_b32 v163, v171, v163, v134
	v_perm_b32 v164, v172, v164, v134
	v_perm_b32 v165, v173, v165, v134
	v_perm_b32 v166, v174, v166, v134
	v_perm_b32 v167, v175, v167, v134
	v_add_u32_e32 v140, 0x18000, v136
	v_add_u32_e32 v141, 0x19000, v136
	global_store_dword v140, v159, s[100:101]
	global_store_dword v141, v161, s[100:101]
	global_store_dword v140, v162, s[100:101] offset:32
	global_store_dword v141, v163, s[100:101] offset:32
	global_store_dword v140, v164, s[100:101] offset:256
	global_store_dword v141, v165, s[100:101] offset:256
	global_store_dword v140, v166, s[100:101] offset:288
	global_store_dword v141, v167, s[100:101] offset:288
	v_add_f32_dpp v151, v151, v151 row_ror:8 row_mask:0xf bank_mask:0xf bound_ctrl:1
	v_add_f32_dpp v152, v152, v152 row_ror:8 row_mask:0xf bank_mask:0xf bound_ctrl:1
	v_add_f32_dpp v153, v153, v153 row_ror:8 row_mask:0xf bank_mask:0xf bound_ctrl:1
	v_add_f32_dpp v154, v154, v154 row_ror:8 row_mask:0xf bank_mask:0xf bound_ctrl:1
	v_add_f32_dpp v151, v151, v151 row_ror:4 row_mask:0xf bank_mask:0xf bound_ctrl:1
	v_add_f32_dpp v152, v152, v152 row_ror:4 row_mask:0xf bank_mask:0xf bound_ctrl:1
	v_add_f32_dpp v153, v153, v153 row_ror:4 row_mask:0xf bank_mask:0xf bound_ctrl:1
	v_add_f32_dpp v154, v154, v154 row_ror:4 row_mask:0xf bank_mask:0xf bound_ctrl:1
	v_add_f32_dpp v151, v151, v151 row_ror:2 row_mask:0xf bank_mask:0xf bound_ctrl:1
	v_add_f32_dpp v152, v152, v152 row_ror:2 row_mask:0xf bank_mask:0xf bound_ctrl:1
	v_add_f32_dpp v153, v153, v153 row_ror:2 row_mask:0xf bank_mask:0xf bound_ctrl:1
	v_add_f32_dpp v154, v154, v154 row_ror:2 row_mask:0xf bank_mask:0xf bound_ctrl:1
	v_mov_b32_dpp v155, v151 row_ror:1 row_mask:0xf bank_mask:0xf bound_ctrl:1
	v_mov_b32_dpp v156, v152 row_ror:1 row_mask:0xf bank_mask:0xf bound_ctrl:1
	v_mov_b32_dpp v157, v153 row_ror:1 row_mask:0xf bank_mask:0xf bound_ctrl:1
	v_mov_b32_dpp v158, v154 row_ror:1 row_mask:0xf bank_mask:0xf bound_ctrl:1
	s_mov_b64 exec, s[0:1]
	v_add_f32_e32 v151, v151, v155
	v_add_f32_e32 v152, v152, v156
	v_add_f32_e32 v153, v153, v157
	v_add_f32_e32 v154, v154, v158
	global_store_dword v137, v151, s[2:3] offset:3072
	global_store_dword v137, v152, s[2:3] offset:3136
	global_store_dword v137, v153, s[2:3] offset:3200
	global_store_dword v137, v154, s[2:3] offset:3264
	s_mov_b64 exec, -1
	s_waitcnt vmcnt(63)
;   __device__ __forceinline__ void operator()(f32x4 (&acc)[2][2][4][2], int brow, int bcol, int wr, int wc, int fr, int fq) const {
;     ...
;     for (int ch = 0; ch < 8; ++ch) {
;       const int ai = ch >> 2, m = ch & 3;
;       int row0 = brow + ai * 128 + wr * 64 + m * 16 + fq * 4;
;       if (ch + 1 < 8) {
;         const float* xbn = xrow(p, brow + ((ch + 1) >> 2) * 128 + wr * 64 + ((ch + 1) & 3) * 16 + fq * 4);
; #pragma unroll
;         for (int q = 0; q < 4; ++q)
; #pragma unroll
;           for (int pr = 0; pr < 2; ++pr)
;             tn[q][pr] = *(const float2*)(xbn + (size_t)(2 * pr + o1) * 1024 + (bcol + (q >> 1) * 128 + wc * 32 + (q & 1) * 16 + fr - o1));
;       }
;       __builtin_amdgcn_sched_barrier(0);
;       float sq[4] = {0.f, 0.f, 0.f, 0.f};
; #pragma unroll
;       for (int q = 0; q < 4; ++q) {
;         const int bj = q >> 1, n = q & 1;
;         int c = bcol + bj * 128 + wc * 32 + n * 16 + fr;
;         float v[4];
; #pragma unroll
;         for (int pr = 0; pr < 2; ++pr) {
;           float2 t = tc[q][pr];
;           float r = dpp_swap1(odd ? t.x : t.y);
;           v[2 * pr] = odd ? r : t.x; v[2 * pr + 1] = odd ? t.y : r;
;         }
; #pragma unroll
;         for (int j = 0; j < 4; ++j) { v[j] += acc[ai][bj][m][n][j]; sq[j] += v[j] * v[j]; }
;         store_rm4(x1b, 1024, row0, c, v[0], v[1], v[2], v[3], odd);
;       }
; #pragma unroll
;       for (int j = 0; j < 4; ++j) {
;         float t = row16_sum(sq[j]);
;         if (fr == 0) ssq1[(size_t)(row0 + j) * 16 + slot] = t;
;       }
;       __builtin_amdgcn_sched_barrier(0);
; #pragma unroll
;       for (int q = 0; q < 4; ++q) { tc[q][0] = tn[q][0]; tc[q][1] = tn[q][1]; }
;     }
	v_cndmask_b32_e32 v143, v241, v240, vcc
	v_cndmask_b32_e32 v144, v243, v242, vcc
	v_cndmask_b32_e32 v145, v245, v244, vcc
	v_cndmask_b32_e32 v146, v247, v246, vcc
	v_cndmask_b32_e32 v147, v249, v248, vcc
	v_cndmask_b32_e32 v148, v251, v250, vcc
	v_cndmask_b32_e32 v149, v253, v252, vcc
	v_cndmask_b32_e32 v150, v255, v254, vcc
	v_mov_b32_dpp v143, v143 quad_perm:[1,0,3,2] row_mask:0xf bank_mask:0xf bound_ctrl:1
	v_mov_b32_dpp v144, v144 quad_perm:[1,0,3,2] row_mask:0xf bank_mask:0xf bound_ctrl:1
	v_mov_b32_dpp v145, v145 quad_perm:[1,0,3,2] row_mask:0xf bank_mask:0xf bound_ctrl:1
	v_mov_b32_dpp v146, v146 quad_perm:[1,0,3,2] row_mask:0xf bank_mask:0xf bound_ctrl:1
	v_mov_b32_dpp v147, v147 quad_perm:[1,0,3,2] row_mask:0xf bank_mask:0xf bound_ctrl:1
	v_mov_b32_dpp v148, v148 quad_perm:[1,0,3,2] row_mask:0xf bank_mask:0xf bound_ctrl:1
	v_mov_b32_dpp v149, v149 quad_perm:[1,0,3,2] row_mask:0xf bank_mask:0xf bound_ctrl:1
	v_mov_b32_dpp v150, v150 quad_perm:[1,0,3,2] row_mask:0xf bank_mask:0xf bound_ctrl:1
	v_cndmask_b32_e32 v240, v240, v143, vcc
	v_cndmask_b32_e32 v241, v143, v241, vcc
	v_cndmask_b32_e32 v242, v242, v144, vcc
	v_cndmask_b32_e32 v243, v144, v243, vcc
	v_cndmask_b32_e32 v244, v244, v145, vcc
	v_cndmask_b32_e32 v245, v145, v245, vcc
	v_cndmask_b32_e32 v246, v246, v146, vcc
	v_cndmask_b32_e32 v247, v146, v247, vcc
	v_cndmask_b32_e32 v248, v248, v147, vcc
	v_cndmask_b32_e32 v249, v147, v249, vcc
	v_cndmask_b32_e32 v250, v250, v148, vcc
	v_cndmask_b32_e32 v251, v148, v251, vcc
	v_cndmask_b32_e32 v252, v252, v149, vcc
	v_cndmask_b32_e32 v253, v149, v253, vcc
	v_cndmask_b32_e32 v254, v254, v150, vcc
	v_cndmask_b32_e32 v255, v150, v255, vcc
	v_add_f32_e32 v60, v60, v240
	v_add_f32_e32 v61, v61, v241
	v_add_f32_e32 v62, v62, v242
	v_add_f32_e32 v63, v63, v243
	v_add_f32_e32 v56, v56, v244
	v_add_f32_e32 v57, v57, v245
	v_add_f32_e32 v58, v58, v246
	v_add_f32_e32 v59, v59, v247
	v_add_f32_e32 v52, v52, v248
	v_add_f32_e32 v53, v53, v249
	v_add_f32_e32 v54, v54, v250
	v_add_f32_e32 v55, v55, v251
	v_add_f32_e32 v48, v48, v252
	v_add_f32_e32 v49, v49, v253
	v_add_f32_e32 v50, v50, v254
	v_add_f32_e32 v51, v51, v255
	v_mul_f32_e32 v151, v60, v60
	v_mul_f32_e32 v152, v61, v61
	v_mul_f32_e32 v153, v62, v62
	v_mul_f32_e32 v154, v63, v63
	v_fmac_f32_e32 v151, v56, v56
	v_fmac_f32_e32 v152, v57, v57
	v_fmac_f32_e32 v153, v58, v58
	v_fmac_f32_e32 v154, v59, v59
	v_fmac_f32_e32 v151, v52, v52
	v_fmac_f32_e32 v152, v53, v53
	v_fmac_f32_e32 v153, v54, v54
	v_fmac_f32_e32 v154, v55, v55
	v_fmac_f32_e32 v151, v48, v48
	v_fmac_f32_e32 v152, v49, v49
	v_fmac_f32_e32 v153, v50, v50
	v_fmac_f32_e32 v154, v51, v51
	v_cvt_pk_bf16_f32 v159, v60, v61
	v_cvt_pk_bf16_f32 v161, v62, v63
	v_cvt_pk_bf16_f32 v162, v56, v57
	v_cvt_pk_bf16_f32 v163, v58, v59
	v_cvt_pk_bf16_f32 v164, v52, v53
	v_cvt_pk_bf16_f32 v165, v54, v55
	v_cvt_pk_bf16_f32 v166, v48, v49
	v_cvt_pk_bf16_f32 v167, v50, v51
	v_mov_b32_dpp v168, v159 quad_perm:[1,0,3,2] row_mask:0xf bank_mask:0xf bound_ctrl:1
	v_mov_b32_dpp v169, v161 quad_perm:[1,0,3,2] row_mask:0xf bank_mask:0xf bound_ctrl:1
	v_mov_b32_dpp v170, v162 quad_perm:[1,0,3,2] row_mask:0xf bank_mask:0xf bound_ctrl:1
	v_mov_b32_dpp v171, v163 quad_perm:[1,0,3,2] row_mask:0xf bank_mask:0xf bound_ctrl:1
	v_mov_b32_dpp v172, v164 quad_perm:[1,0,3,2] row_mask:0xf bank_mask:0xf bound_ctrl:1
	v_mov_b32_dpp v173, v165 quad_perm:[1,0,3,2] row_mask:0xf bank_mask:0xf bound_ctrl:1
	v_mov_b32_dpp v174, v166 quad_perm:[1,0,3,2] row_mask:0xf bank_mask:0xf bound_ctrl:1
	v_mov_b32_dpp v175, v167 quad_perm:[1,0,3,2] row_mask:0xf bank_mask:0xf bound_ctrl:1
	v_perm_b32 v159, v168, v159, v134
	v_perm_b32 v161, v169, v161, v134
	v_perm_b32 v162, v170, v162, v134
	v_perm_b32 v163, v171, v163, v134
	v_perm_b32 v164, v172, v164, v134
	v_perm_b32 v165, v173, v165, v134
	v_perm_b32 v166, v174, v166, v134
	v_perm_b32 v167, v175, v167, v134
	v_add_u32_e32 v140, 0x40000, v136
	v_add_u32_e32 v141, 0x41000, v136
	global_store_dword v140, v159, s[100:101]
	global_store_dword v141, v161, s[100:101]
	global_store_dword v140, v162, s[100:101] offset:32
	global_store_dword v141, v163, s[100:101] offset:32
	global_store_dword v140, v164, s[100:101] offset:256
	global_store_dword v141, v165, s[100:101] offset:256
	global_store_dword v140, v166, s[100:101] offset:288
	global_store_dword v141, v167, s[100:101] offset:288
	v_add_f32_dpp v151, v151, v151 row_ror:8 row_mask:0xf bank_mask:0xf bound_ctrl:1
	v_add_f32_dpp v152, v152, v152 row_ror:8 row_mask:0xf bank_mask:0xf bound_ctrl:1
	v_add_f32_dpp v153, v153, v153 row_ror:8 row_mask:0xf bank_mask:0xf bound_ctrl:1
	v_add_f32_dpp v154, v154, v154 row_ror:8 row_mask:0xf bank_mask:0xf bound_ctrl:1
	v_add_f32_dpp v151, v151, v151 row_ror:4 row_mask:0xf bank_mask:0xf bound_ctrl:1
	v_add_f32_dpp v152, v152, v152 row_ror:4 row_mask:0xf bank_mask:0xf bound_ctrl:1
	v_add_f32_dpp v153, v153, v153 row_ror:4 row_mask:0xf bank_mask:0xf bound_ctrl:1
	v_add_f32_dpp v154, v154, v154 row_ror:4 row_mask:0xf bank_mask:0xf bound_ctrl:1
	v_add_f32_dpp v151, v151, v151 row_ror:2 row_mask:0xf bank_mask:0xf bound_ctrl:1
	v_add_f32_dpp v152, v152, v152 row_ror:2 row_mask:0xf bank_mask:0xf bound_ctrl:1
	v_add_f32_dpp v153, v153, v153 row_ror:2 row_mask:0xf bank_mask:0xf bound_ctrl:1
	v_add_f32_dpp v154, v154, v154 row_ror:2 row_mask:0xf bank_mask:0xf bound_ctrl:1
	v_mov_b32_dpp v155, v151 row_ror:1 row_mask:0xf bank_mask:0xf bound_ctrl:1
	v_mov_b32_dpp v156, v152 row_ror:1 row_mask:0xf bank_mask:0xf bound_ctrl:1
	v_mov_b32_dpp v157, v153 row_ror:1 row_mask:0xf bank_mask:0xf bound_ctrl:1
	v_mov_b32_dpp v158, v154 row_ror:1 row_mask:0xf bank_mask:0xf bound_ctrl:1
	v_add_u32_e32 v142, 0x2000, v137
	s_mov_b64 exec, s[0:1]
	v_add_f32_e32 v151, v151, v155
	v_add_f32_e32 v152, v152, v156
	v_add_f32_e32 v153, v153, v157
	v_add_f32_e32 v154, v154, v158
	global_store_dword v142, v151, s[2:3] offset:0
	global_store_dword v142, v152, s[2:3] offset:64
	global_store_dword v142, v153, s[2:3] offset:128
	global_store_dword v142, v154, s[2:3] offset:192
	s_mov_b64 exec, -1
	s_waitcnt vmcnt(63)
; __device__ __forceinline__ void store_rm4(u16* dst, size_t ld, int row0, int c, float v0, float v1, float v2, float v3, bool odd) {
;   {
;     float s = odd ? v0 : v1, r = dpp_swap1(s);
;     float lo = odd ? r : v0, hi = odd ? v1 : r;
;     *(unsigned*)(dst + (size_t)(row0 + (odd ? 1 : 0)) * ld + (c - (odd ? 1 : 0))) = pack2(lo, hi);
;   }
;   {
;     float s = odd ? v2 : v3, r = dpp_swap1(s);
;     float lo = odd ? r : v2, hi = odd ? v3 : r;
;     *(unsigned*)(dst + (size_t)(row0 + 2 + (odd ? 1 : 0)) * ld + (c - (odd ? 1 : 0))) = pack2(lo, hi);
;   }
;   __device__ __forceinline__ void operator()(f32x4 (&acc)[2][2][4][2], int brow, int bcol, int wr, int wc, int fr, int fq) const {
;     ...
; #pragma unroll
;       for (int q = 0; q < 4; ++q) {
;         const int bj = q >> 1, n = q & 1;
;         int c = bcol + bj * 128 + wc * 32 + n * 16 + fr;
;         float v[4];
; #pragma unroll
;         for (int pr = 0; pr < 2; ++pr) {
;           float2 t = tc[q][pr];
;           float r = dpp_swap1(odd ? t.x : t.y);
;           v[2 * pr] = odd ? r : t.x; v[2 * pr + 1] = odd ? t.y : r;
;         }
; #pragma unroll
;         for (int j = 0; j < 4; ++j) { v[j] += acc[ai][bj][m][n][j]; sq[j] += v[j] * v[j]; }
;         store_rm4(x1b, 1024, row0, c, v[0], v[1], v[2], v[3], odd);
;       }
; #pragma unroll
;       for (int j = 0; j < 4; ++j) {
;         float t = row16_sum(sq[j]);
;         if (fr == 0) ssq1[(size_t)(row0 + j) * 16 + slot] = t;
;       }
	v_cndmask_b32_e32 v143, v177, v176, vcc
	v_cndmask_b32_e32 v144, v179, v178, vcc
	v_cndmask_b32_e32 v145, v181, v180, vcc
	v_cndmask_b32_e32 v146, v183, v182, vcc
	v_cndmask_b32_e32 v147, v185, v184, vcc
	v_cndmask_b32_e32 v148, v187, v186, vcc
	v_cndmask_b32_e32 v149, v189, v188, vcc
	v_cndmask_b32_e32 v150, v191, v190, vcc
	v_mov_b32_dpp v143, v143 quad_perm:[1,0,3,2] row_mask:0xf bank_mask:0xf bound_ctrl:1
	v_mov_b32_dpp v144, v144 quad_perm:[1,0,3,2] row_mask:0xf bank_mask:0xf bound_ctrl:1
	v_mov_b32_dpp v145, v145 quad_perm:[1,0,3,2] row_mask:0xf bank_mask:0xf bound_ctrl:1
	v_mov_b32_dpp v146, v146 quad_perm:[1,0,3,2] row_mask:0xf bank_mask:0xf bound_ctrl:1
	v_mov_b32_dpp v147, v147 quad_perm:[1,0,3,2] row_mask:0xf bank_mask:0xf bound_ctrl:1
	v_mov_b32_dpp v148, v148 quad_perm:[1,0,3,2] row_mask:0xf bank_mask:0xf bound_ctrl:1
	v_mov_b32_dpp v149, v149 quad_perm:[1,0,3,2] row_mask:0xf bank_mask:0xf bound_ctrl:1
	v_mov_b32_dpp v150, v150 quad_perm:[1,0,3,2] row_mask:0xf bank_mask:0xf bound_ctrl:1
	v_cndmask_b32_e32 v176, v176, v143, vcc
	v_cndmask_b32_e32 v177, v143, v177, vcc
	v_cndmask_b32_e32 v178, v178, v144, vcc
	v_cndmask_b32_e32 v179, v144, v179, vcc
	v_cndmask_b32_e32 v180, v180, v145, vcc
	v_cndmask_b32_e32 v181, v145, v181, vcc
	v_cndmask_b32_e32 v182, v182, v146, vcc
	v_cndmask_b32_e32 v183, v146, v183, vcc
	v_cndmask_b32_e32 v184, v184, v147, vcc
	v_cndmask_b32_e32 v185, v147, v185, vcc
	v_cndmask_b32_e32 v186, v186, v148, vcc
	v_cndmask_b32_e32 v187, v148, v187, vcc
	v_cndmask_b32_e32 v188, v188, v149, vcc
	v_cndmask_b32_e32 v189, v149, v189, vcc
	v_cndmask_b32_e32 v190, v190, v150, vcc
	v_cndmask_b32_e32 v191, v150, v191, vcc
	v_add_f32_e32 v44, v44, v176
	v_add_f32_e32 v45, v45, v177
	v_add_f32_e32 v46, v46, v178
	v_add_f32_e32 v47, v47, v179
	v_add_f32_e32 v40, v40, v180
	v_add_f32_e32 v41, v41, v181
	v_add_f32_e32 v42, v42, v182
	v_add_f32_e32 v43, v43, v183
	v_add_f32_e32 v36, v36, v184
	v_add_f32_e32 v37, v37, v185
	v_add_f32_e32 v38, v38, v186
	v_add_f32_e32 v39, v39, v187
	v_add_f32_e32 v32, v32, v188
	v_add_f32_e32 v33, v33, v189
	v_add_f32_e32 v34, v34, v190
	v_add_f32_e32 v35, v35, v191
	v_mul_f32_e32 v151, v44, v44
	v_mul_f32_e32 v152, v45, v45
	v_mul_f32_e32 v153, v46, v46
	v_mul_f32_e32 v154, v47, v47
	v_fmac_f32_e32 v151, v40, v40
	v_fmac_f32_e32 v152, v41, v41
	v_fmac_f32_e32 v153, v42, v42
	v_fmac_f32_e32 v154, v43, v43
	v_fmac_f32_e32 v151, v36, v36
	v_fmac_f32_e32 v152, v37, v37
	v_fmac_f32_e32 v153, v38, v38
	v_fmac_f32_e32 v154, v39, v39
	v_fmac_f32_e32 v151, v32, v32
	v_fmac_f32_e32 v152, v33, v33
	v_fmac_f32_e32 v153, v34, v34
	v_fmac_f32_e32 v154, v35, v35
	v_cvt_pk_bf16_f32 v159, v44, v45
	v_cvt_pk_bf16_f32 v161, v46, v47
	v_cvt_pk_bf16_f32 v162, v40, v41
	v_cvt_pk_bf16_f32 v163, v42, v43
	v_cvt_pk_bf16_f32 v164, v36, v37
	v_cvt_pk_bf16_f32 v165, v38, v39
	v_cvt_pk_bf16_f32 v166, v32, v33
	v_cvt_pk_bf16_f32 v167, v34, v35
	v_mov_b32_dpp v168, v159 quad_perm:[1,0,3,2] row_mask:0xf bank_mask:0xf bound_ctrl:1
	v_mov_b32_dpp v169, v161 quad_perm:[1,0,3,2] row_mask:0xf bank_mask:0xf bound_ctrl:1
	v_mov_b32_dpp v170, v162 quad_perm:[1,0,3,2] row_mask:0xf bank_mask:0xf bound_ctrl:1
	v_mov_b32_dpp v171, v163 quad_perm:[1,0,3,2] row_mask:0xf bank_mask:0xf bound_ctrl:1
	v_mov_b32_dpp v172, v164 quad_perm:[1,0,3,2] row_mask:0xf bank_mask:0xf bound_ctrl:1
	v_mov_b32_dpp v173, v165 quad_perm:[1,0,3,2] row_mask:0xf bank_mask:0xf bound_ctrl:1
	v_mov_b32_dpp v174, v166 quad_perm:[1,0,3,2] row_mask:0xf bank_mask:0xf bound_ctrl:1
	v_mov_b32_dpp v175, v167 quad_perm:[1,0,3,2] row_mask:0xf bank_mask:0xf bound_ctrl:1
	v_perm_b32 v159, v168, v159, v134
	v_perm_b32 v161, v169, v161, v134
	v_perm_b32 v162, v170, v162, v134
	v_perm_b32 v163, v171, v163, v134
	v_perm_b32 v164, v172, v164, v134
	v_perm_b32 v165, v173, v165, v134
	v_perm_b32 v166, v174, v166, v134
	v_perm_b32 v167, v175, v167, v134
	v_add_u32_e32 v140, 0x48000, v136
	v_add_u32_e32 v141, 0x49000, v136
	global_store_dword v140, v159, s[100:101]
	global_store_dword v141, v161, s[100:101]
	global_store_dword v140, v162, s[100:101] offset:32
	global_store_dword v141, v163, s[100:101] offset:32
	global_store_dword v140, v164, s[100:101] offset:256
	global_store_dword v141, v165, s[100:101] offset:256
	global_store_dword v140, v166, s[100:101] offset:288
	global_store_dword v141, v167, s[100:101] offset:288
	v_add_f32_dpp v151, v151, v151 row_ror:8 row_mask:0xf bank_mask:0xf bound_ctrl:1
	v_add_f32_dpp v152, v152, v152 row_ror:8 row_mask:0xf bank_mask:0xf bound_ctrl:1
	v_add_f32_dpp v153, v153, v153 row_ror:8 row_mask:0xf bank_mask:0xf bound_ctrl:1
	v_add_f32_dpp v154, v154, v154 row_ror:8 row_mask:0xf bank_mask:0xf bound_ctrl:1
	v_add_f32_dpp v151, v151, v151 row_ror:4 row_mask:0xf bank_mask:0xf bound_ctrl:1
	v_add_f32_dpp v152, v152, v152 row_ror:4 row_mask:0xf bank_mask:0xf bound_ctrl:1
	v_add_f32_dpp v153, v153, v153 row_ror:4 row_mask:0xf bank_mask:0xf bound_ctrl:1
	v_add_f32_dpp v154, v154, v154 row_ror:4 row_mask:0xf bank_mask:0xf bound_ctrl:1
	v_add_f32_dpp v151, v151, v151 row_ror:2 row_mask:0xf bank_mask:0xf bound_ctrl:1
	v_add_f32_dpp v152, v152, v152 row_ror:2 row_mask:0xf bank_mask:0xf bound_ctrl:1
	v_add_f32_dpp v153, v153, v153 row_ror:2 row_mask:0xf bank_mask:0xf bound_ctrl:1
	v_add_f32_dpp v154, v154, v154 row_ror:2 row_mask:0xf bank_mask:0xf bound_ctrl:1
	v_mov_b32_dpp v155, v151 row_ror:1 row_mask:0xf bank_mask:0xf bound_ctrl:1
	v_mov_b32_dpp v156, v152 row_ror:1 row_mask:0xf bank_mask:0xf bound_ctrl:1
	v_mov_b32_dpp v157, v153 row_ror:1 row_mask:0xf bank_mask:0xf bound_ctrl:1
	v_mov_b32_dpp v158, v154 row_ror:1 row_mask:0xf bank_mask:0xf bound_ctrl:1
	v_add_u32_e32 v142, 0x2000, v137
	s_mov_b64 exec, s[0:1]
	v_add_f32_e32 v151, v151, v155
	v_add_f32_e32 v152, v152, v156
	v_add_f32_e32 v153, v153, v157
	v_add_f32_e32 v154, v154, v158
	global_store_dword v142, v151, s[2:3] offset:1024
	global_store_dword v142, v152, s[2:3] offset:1088
	global_store_dword v142, v153, s[2:3] offset:1152
	global_store_dword v142, v154, s[2:3] offset:1216
	s_mov_b64 exec, -1
	s_waitcnt vmcnt(56)
; __device__ __forceinline__ void store_rm4(u16* dst, size_t ld, int row0, int c, float v0, float v1, float v2, float v3, bool odd) {
;   {
;     float s = odd ? v0 : v1, r = dpp_swap1(s);
;     float lo = odd ? r : v0, hi = odd ? v1 : r;
;     *(unsigned*)(dst + (size_t)(row0 + (odd ? 1 : 0)) * ld + (c - (odd ? 1 : 0))) = pack2(lo, hi);
;   }
;   {
;     float s = odd ? v2 : v3, r = dpp_swap1(s);
;     float lo = odd ? r : v2, hi = odd ? v3 : r;
;     *(unsigned*)(dst + (size_t)(row0 + 2 + (odd ? 1 : 0)) * ld + (c - (odd ? 1 : 0))) = pack2(lo, hi);
;   }
;   __device__ __forceinline__ void operator()(f32x4 (&acc)[2][2][4][2], int brow, int bcol, int wr, int wc, int fr, int fq) const {
;     ...
; #pragma unroll
;       for (int q = 0; q < 4; ++q) {
;         const int bj = q >> 1, n = q & 1;
;         int c = bcol + bj * 128 + wc * 32 + n * 16 + fr;
;         float v[4];
; #pragma unroll
;         for (int pr = 0; pr < 2; ++pr) {
;           float2 t = tc[q][pr];
;           float r = dpp_swap1(odd ? t.x : t.y);
;           v[2 * pr] = odd ? r : t.x; v[2 * pr + 1] = odd ? t.y : r;
;         }
; #pragma unroll
;         for (int j = 0; j < 4; ++j) { v[j] += acc[ai][bj][m][n][j]; sq[j] += v[j] * v[j]; }
;         store_rm4(x1b, 1024, row0, c, v[0], v[1], v[2], v[3], odd);
;       }
; #pragma unroll
;       for (int j = 0; j < 4; ++j) {
;         float t = row16_sum(sq[j]);
;         if (fr == 0) ssq1[(size_t)(row0 + j) * 16 + slot] = t;
;       }
	v_cndmask_b32_e32 v143, v193, v192, vcc
	v_cndmask_b32_e32 v144, v195, v194, vcc
	v_cndmask_b32_e32 v145, v197, v196, vcc
	v_cndmask_b32_e32 v146, v199, v198, vcc
	v_cndmask_b32_e32 v147, v201, v200, vcc
	v_cndmask_b32_e32 v148, v203, v202, vcc
	v_cndmask_b32_e32 v149, v205, v204, vcc
	v_cndmask_b32_e32 v150, v207, v206, vcc
	v_mov_b32_dpp v143, v143 quad_perm:[1,0,3,2] row_mask:0xf bank_mask:0xf bound_ctrl:1
	v_mov_b32_dpp v144, v144 quad_perm:[1,0,3,2] row_mask:0xf bank_mask:0xf bound_ctrl:1
	v_mov_b32_dpp v145, v145 quad_perm:[1,0,3,2] row_mask:0xf bank_mask:0xf bound_ctrl:1
	v_mov_b32_dpp v146, v146 quad_perm:[1,0,3,2] row_mask:0xf bank_mask:0xf bound_ctrl:1
	v_mov_b32_dpp v147, v147 quad_perm:[1,0,3,2] row_mask:0xf bank_mask:0xf bound_ctrl:1
	v_mov_b32_dpp v148, v148 quad_perm:[1,0,3,2] row_mask:0xf bank_mask:0xf bound_ctrl:1
	v_mov_b32_dpp v149, v149 quad_perm:[1,0,3,2] row_mask:0xf bank_mask:0xf bound_ctrl:1
	v_mov_b32_dpp v150, v150 quad_perm:[1,0,3,2] row_mask:0xf bank_mask:0xf bound_ctrl:1
	v_cndmask_b32_e32 v192, v192, v143, vcc
	v_cndmask_b32_e32 v193, v143, v193, vcc
	v_cndmask_b32_e32 v194, v194, v144, vcc
	v_cndmask_b32_e32 v195, v144, v195, vcc
	v_cndmask_b32_e32 v196, v196, v145, vcc
	v_cndmask_b32_e32 v197, v145, v197, vcc
	v_cndmask_b32_e32 v198, v198, v146, vcc
	v_cndmask_b32_e32 v199, v146, v199, vcc
	v_cndmask_b32_e32 v200, v200, v147, vcc
	v_cndmask_b32_e32 v201, v147, v201, vcc
	v_cndmask_b32_e32 v202, v202, v148, vcc
	v_cndmask_b32_e32 v203, v148, v203, vcc
	v_cndmask_b32_e32 v204, v204, v149, vcc
	v_cndmask_b32_e32 v205, v149, v205, vcc
	v_cndmask_b32_e32 v206, v206, v150, vcc
	v_cndmask_b32_e32 v207, v150, v207, vcc
	v_add_f32_e32 v28, v28, v192
	v_add_f32_e32 v29, v29, v193
	v_add_f32_e32 v30, v30, v194
	v_add_f32_e32 v31, v31, v195
	v_add_f32_e32 v24, v24, v196
	v_add_f32_e32 v25, v25, v197
	v_add_f32_e32 v26, v26, v198
	v_add_f32_e32 v27, v27, v199
	v_add_f32_e32 v20, v20, v200
	v_add_f32_e32 v21, v21, v201
	v_add_f32_e32 v22, v22, v202
	v_add_f32_e32 v23, v23, v203
	v_add_f32_e32 v16, v16, v204
	v_add_f32_e32 v17, v17, v205
	v_add_f32_e32 v18, v18, v206
	v_add_f32_e32 v19, v19, v207
	v_mul_f32_e32 v151, v28, v28
	v_mul_f32_e32 v152, v29, v29
	v_mul_f32_e32 v153, v30, v30
	v_mul_f32_e32 v154, v31, v31
	v_fmac_f32_e32 v151, v24, v24
	v_fmac_f32_e32 v152, v25, v25
	v_fmac_f32_e32 v153, v26, v26
	v_fmac_f32_e32 v154, v27, v27
	v_fmac_f32_e32 v151, v20, v20
	v_fmac_f32_e32 v152, v21, v21
	v_fmac_f32_e32 v153, v22, v22
	v_fmac_f32_e32 v154, v23, v23
	v_fmac_f32_e32 v151, v16, v16
	v_fmac_f32_e32 v152, v17, v17
	v_fmac_f32_e32 v153, v18, v18
	v_fmac_f32_e32 v154, v19, v19
	v_cvt_pk_bf16_f32 v159, v28, v29
	v_cvt_pk_bf16_f32 v161, v30, v31
	v_cvt_pk_bf16_f32 v162, v24, v25
	v_cvt_pk_bf16_f32 v163, v26, v27
	v_cvt_pk_bf16_f32 v164, v20, v21
	v_cvt_pk_bf16_f32 v165, v22, v23
	v_cvt_pk_bf16_f32 v166, v16, v17
	v_cvt_pk_bf16_f32 v167, v18, v19
	v_mov_b32_dpp v168, v159 quad_perm:[1,0,3,2] row_mask:0xf bank_mask:0xf bound_ctrl:1
	v_mov_b32_dpp v169, v161 quad_perm:[1,0,3,2] row_mask:0xf bank_mask:0xf bound_ctrl:1
	v_mov_b32_dpp v170, v162 quad_perm:[1,0,3,2] row_mask:0xf bank_mask:0xf bound_ctrl:1
	v_mov_b32_dpp v171, v163 quad_perm:[1,0,3,2] row_mask:0xf bank_mask:0xf bound_ctrl:1
	v_mov_b32_dpp v172, v164 quad_perm:[1,0,3,2] row_mask:0xf bank_mask:0xf bound_ctrl:1
	v_mov_b32_dpp v173, v165 quad_perm:[1,0,3,2] row_mask:0xf bank_mask:0xf bound_ctrl:1
	v_mov_b32_dpp v174, v166 quad_perm:[1,0,3,2] row_mask:0xf bank_mask:0xf bound_ctrl:1
	v_mov_b32_dpp v175, v167 quad_perm:[1,0,3,2] row_mask:0xf bank_mask:0xf bound_ctrl:1
	v_perm_b32 v159, v168, v159, v134
	v_perm_b32 v161, v169, v161, v134
	v_perm_b32 v162, v170, v162, v134
	v_perm_b32 v163, v171, v163, v134
	v_perm_b32 v164, v172, v164, v134
	v_perm_b32 v165, v173, v165, v134
	v_perm_b32 v166, v174, v166, v134
	v_perm_b32 v167, v175, v167, v134
	v_add_u32_e32 v140, 0x50000, v136
	v_add_u32_e32 v141, 0x51000, v136
	global_store_dword v140, v159, s[100:101]
	global_store_dword v141, v161, s[100:101]
	global_store_dword v140, v162, s[100:101] offset:32
	global_store_dword v141, v163, s[100:101] offset:32
	global_store_dword v140, v164, s[100:101] offset:256
	global_store_dword v141, v165, s[100:101] offset:256
	global_store_dword v140, v166, s[100:101] offset:288
	global_store_dword v141, v167, s[100:101] offset:288
	v_add_f32_dpp v151, v151, v151 row_ror:8 row_mask:0xf bank_mask:0xf bound_ctrl:1
	v_add_f32_dpp v152, v152, v152 row_ror:8 row_mask:0xf bank_mask:0xf bound_ctrl:1
	v_add_f32_dpp v153, v153, v153 row_ror:8 row_mask:0xf bank_mask:0xf bound_ctrl:1
	v_add_f32_dpp v154, v154, v154 row_ror:8 row_mask:0xf bank_mask:0xf bound_ctrl:1
	v_add_f32_dpp v151, v151, v151 row_ror:4 row_mask:0xf bank_mask:0xf bound_ctrl:1
	v_add_f32_dpp v152, v152, v152 row_ror:4 row_mask:0xf bank_mask:0xf bound_ctrl:1
	v_add_f32_dpp v153, v153, v153 row_ror:4 row_mask:0xf bank_mask:0xf bound_ctrl:1
	v_add_f32_dpp v154, v154, v154 row_ror:4 row_mask:0xf bank_mask:0xf bound_ctrl:1
	v_add_f32_dpp v151, v151, v151 row_ror:2 row_mask:0xf bank_mask:0xf bound_ctrl:1
	v_add_f32_dpp v152, v152, v152 row_ror:2 row_mask:0xf bank_mask:0xf bound_ctrl:1
	v_add_f32_dpp v153, v153, v153 row_ror:2 row_mask:0xf bank_mask:0xf bound_ctrl:1
	v_add_f32_dpp v154, v154, v154 row_ror:2 row_mask:0xf bank_mask:0xf bound_ctrl:1
	v_mov_b32_dpp v155, v151 row_ror:1 row_mask:0xf bank_mask:0xf bound_ctrl:1
	v_mov_b32_dpp v156, v152 row_ror:1 row_mask:0xf bank_mask:0xf bound_ctrl:1
	v_mov_b32_dpp v157, v153 row_ror:1 row_mask:0xf bank_mask:0xf bound_ctrl:1
	v_mov_b32_dpp v158, v154 row_ror:1 row_mask:0xf bank_mask:0xf bound_ctrl:1
	v_add_u32_e32 v142, 0x2000, v137
	s_mov_b64 exec, s[0:1]
	v_add_f32_e32 v151, v151, v155
	v_add_f32_e32 v152, v152, v156
	v_add_f32_e32 v153, v153, v157
	v_add_f32_e32 v154, v154, v158
	global_store_dword v142, v151, s[2:3] offset:2048
	global_store_dword v142, v152, s[2:3] offset:2112
	global_store_dword v142, v153, s[2:3] offset:2176
	global_store_dword v142, v154, s[2:3] offset:2240
	s_mov_b64 exec, -1
	s_waitcnt vmcnt(48)
; __device__ __forceinline__ void store_rm4(u16* dst, size_t ld, int row0, int c, float v0, float v1, float v2, float v3, bool odd) {
;   {
;     float s = odd ? v0 : v1, r = dpp_swap1(s);
;     float lo = odd ? r : v0, hi = odd ? v1 : r;
;     *(unsigned*)(dst + (size_t)(row0 + (odd ? 1 : 0)) * ld + (c - (odd ? 1 : 0))) = pack2(lo, hi);
;   }
;   {
;     float s = odd ? v2 : v3, r = dpp_swap1(s);
;     float lo = odd ? r : v2, hi = odd ? v3 : r;
;     *(unsigned*)(dst + (size_t)(row0 + 2 + (odd ? 1 : 0)) * ld + (c - (odd ? 1 : 0))) = pack2(lo, hi);
;   }
;   __device__ __forceinline__ void operator()(f32x4 (&acc)[2][2][4][2], int brow, int bcol, int wr, int wc, int fr, int fq) const {
;     ...
; #pragma unroll
;       for (int q = 0; q < 4; ++q) {
;         const int bj = q >> 1, n = q & 1;
;         int c = bcol + bj * 128 + wc * 32 + n * 16 + fr;
;         float v[4];
; #pragma unroll
;         for (int pr = 0; pr < 2; ++pr) {
;           float2 t = tc[q][pr];
;           float r = dpp_swap1(odd ? t.x : t.y);
;           v[2 * pr] = odd ? r : t.x; v[2 * pr + 1] = odd ? t.y : r;
;         }
; #pragma unroll
;         for (int j = 0; j < 4; ++j) { v[j] += acc[ai][bj][m][n][j]; sq[j] += v[j] * v[j]; }
;         store_rm4(x1b, 1024, row0, c, v[0], v[1], v[2], v[3], odd);
;       }
; #pragma unroll
;       for (int j = 0; j < 4; ++j) {
;         float t = row16_sum(sq[j]);
;         if (fr == 0) ssq1[(size_t)(row0 + j) * 16 + slot] = t;
;       }
;       __builtin_amdgcn_sched_barrier(0);
; #pragma unroll
;       for (int q = 0; q < 4; ++q) { tc[q][0] = tn[q][0]; tc[q][1] = tn[q][1]; }
	v_cndmask_b32_e32 v143, v209, v208, vcc
	v_cndmask_b32_e32 v144, v211, v210, vcc
	v_cndmask_b32_e32 v145, v213, v212, vcc
	v_cndmask_b32_e32 v146, v215, v214, vcc
	v_cndmask_b32_e32 v147, v217, v216, vcc
	v_cndmask_b32_e32 v148, v219, v218, vcc
	v_cndmask_b32_e32 v149, v221, v220, vcc
	v_cndmask_b32_e32 v150, v223, v222, vcc
	v_mov_b32_dpp v143, v143 quad_perm:[1,0,3,2] row_mask:0xf bank_mask:0xf bound_ctrl:1
	v_mov_b32_dpp v144, v144 quad_perm:[1,0,3,2] row_mask:0xf bank_mask:0xf bound_ctrl:1
	v_mov_b32_dpp v145, v145 quad_perm:[1,0,3,2] row_mask:0xf bank_mask:0xf bound_ctrl:1
	v_mov_b32_dpp v146, v146 quad_perm:[1,0,3,2] row_mask:0xf bank_mask:0xf bound_ctrl:1
	v_mov_b32_dpp v147, v147 quad_perm:[1,0,3,2] row_mask:0xf bank_mask:0xf bound_ctrl:1
	v_mov_b32_dpp v148, v148 quad_perm:[1,0,3,2] row_mask:0xf bank_mask:0xf bound_ctrl:1
	v_mov_b32_dpp v149, v149 quad_perm:[1,0,3,2] row_mask:0xf bank_mask:0xf bound_ctrl:1
	v_mov_b32_dpp v150, v150 quad_perm:[1,0,3,2] row_mask:0xf bank_mask:0xf bound_ctrl:1
	v_cndmask_b32_e32 v208, v208, v143, vcc
	v_cndmask_b32_e32 v209, v143, v209, vcc
	v_cndmask_b32_e32 v210, v210, v144, vcc
	v_cndmask_b32_e32 v211, v144, v211, vcc
	v_cndmask_b32_e32 v212, v212, v145, vcc
	v_cndmask_b32_e32 v213, v145, v213, vcc
	v_cndmask_b32_e32 v214, v214, v146, vcc
	v_cndmask_b32_e32 v215, v146, v215, vcc
	v_cndmask_b32_e32 v216, v216, v147, vcc
	v_cndmask_b32_e32 v217, v147, v217, vcc
	v_cndmask_b32_e32 v218, v218, v148, vcc
	v_cndmask_b32_e32 v219, v148, v219, vcc
	v_cndmask_b32_e32 v220, v220, v149, vcc
	v_cndmask_b32_e32 v221, v149, v221, vcc
	v_cndmask_b32_e32 v222, v222, v150, vcc
	v_cndmask_b32_e32 v223, v150, v223, vcc
	v_add_f32_e32 v12, v12, v208
	v_add_f32_e32 v13, v13, v209
	v_add_f32_e32 v14, v14, v210
	v_add_f32_e32 v15, v15, v211
	v_add_f32_e32 v8, v8, v212
	v_add_f32_e32 v9, v9, v213
	v_add_f32_e32 v10, v10, v214
	v_add_f32_e32 v11, v11, v215
	v_add_f32_e32 v4, v4, v216
	v_add_f32_e32 v5, v5, v217
	v_add_f32_e32 v6, v6, v218
	v_add_f32_e32 v7, v7, v219
	v_add_f32_e32 v0, v0, v220
	v_add_f32_e32 v1, v1, v221
	v_add_f32_e32 v2, v2, v222
	v_add_f32_e32 v3, v3, v223
	v_mul_f32_e32 v151, v12, v12
	v_mul_f32_e32 v152, v13, v13
	v_mul_f32_e32 v153, v14, v14
	v_mul_f32_e32 v154, v15, v15
	v_fmac_f32_e32 v151, v8, v8
	v_fmac_f32_e32 v152, v9, v9
	v_fmac_f32_e32 v153, v10, v10
	v_fmac_f32_e32 v154, v11, v11
	v_fmac_f32_e32 v151, v4, v4
	v_fmac_f32_e32 v152, v5, v5
	v_fmac_f32_e32 v153, v6, v6
	v_fmac_f32_e32 v154, v7, v7
	v_fmac_f32_e32 v151, v0, v0
	v_fmac_f32_e32 v152, v1, v1
	v_fmac_f32_e32 v153, v2, v2
	v_fmac_f32_e32 v154, v3, v3
	v_cvt_pk_bf16_f32 v159, v12, v13
	v_cvt_pk_bf16_f32 v161, v14, v15
	v_cvt_pk_bf16_f32 v162, v8, v9
	v_cvt_pk_bf16_f32 v163, v10, v11
	v_cvt_pk_bf16_f32 v164, v4, v5
	v_cvt_pk_bf16_f32 v165, v6, v7
	v_cvt_pk_bf16_f32 v166, v0, v1
	v_cvt_pk_bf16_f32 v167, v2, v3
	v_mov_b32_dpp v168, v159 quad_perm:[1,0,3,2] row_mask:0xf bank_mask:0xf bound_ctrl:1
	v_mov_b32_dpp v169, v161 quad_perm:[1,0,3,2] row_mask:0xf bank_mask:0xf bound_ctrl:1
	v_mov_b32_dpp v170, v162 quad_perm:[1,0,3,2] row_mask:0xf bank_mask:0xf bound_ctrl:1
	v_mov_b32_dpp v171, v163 quad_perm:[1,0,3,2] row_mask:0xf bank_mask:0xf bound_ctrl:1
	v_mov_b32_dpp v172, v164 quad_perm:[1,0,3,2] row_mask:0xf bank_mask:0xf bound_ctrl:1
	v_mov_b32_dpp v173, v165 quad_perm:[1,0,3,2] row_mask:0xf bank_mask:0xf bound_ctrl:1
	v_mov_b32_dpp v174, v166 quad_perm:[1,0,3,2] row_mask:0xf bank_mask:0xf bound_ctrl:1
	v_mov_b32_dpp v175, v167 quad_perm:[1,0,3,2] row_mask:0xf bank_mask:0xf bound_ctrl:1
	v_perm_b32 v159, v168, v159, v134
	v_perm_b32 v161, v169, v161, v134
	v_perm_b32 v162, v170, v162, v134
	v_perm_b32 v163, v171, v163, v134
	v_perm_b32 v164, v172, v164, v134
	v_perm_b32 v165, v173, v165, v134
	v_perm_b32 v166, v174, v166, v134
	v_perm_b32 v167, v175, v167, v134
	v_add_u32_e32 v140, 0x58000, v136
	v_add_u32_e32 v141, 0x59000, v136
	global_store_dword v140, v159, s[100:101]
	global_store_dword v141, v161, s[100:101]
	global_store_dword v140, v162, s[100:101] offset:32
	global_store_dword v141, v163, s[100:101] offset:32
	global_store_dword v140, v164, s[100:101] offset:256
	global_store_dword v141, v165, s[100:101] offset:256
	global_store_dword v140, v166, s[100:101] offset:288
	global_store_dword v141, v167, s[100:101] offset:288
	v_add_f32_dpp v151, v151, v151 row_ror:8 row_mask:0xf bank_mask:0xf bound_ctrl:1
	v_add_f32_dpp v152, v152, v152 row_ror:8 row_mask:0xf bank_mask:0xf bound_ctrl:1
	v_add_f32_dpp v153, v153, v153 row_ror:8 row_mask:0xf bank_mask:0xf bound_ctrl:1
	v_add_f32_dpp v154, v154, v154 row_ror:8 row_mask:0xf bank_mask:0xf bound_ctrl:1
	v_add_f32_dpp v151, v151, v151 row_ror:4 row_mask:0xf bank_mask:0xf bound_ctrl:1
	v_add_f32_dpp v152, v152, v152 row_ror:4 row_mask:0xf bank_mask:0xf bound_ctrl:1
	v_add_f32_dpp v153, v153, v153 row_ror:4 row_mask:0xf bank_mask:0xf bound_ctrl:1
	v_add_f32_dpp v154, v154, v154 row_ror:4 row_mask:0xf bank_mask:0xf bound_ctrl:1
	v_add_f32_dpp v151, v151, v151 row_ror:2 row_mask:0xf bank_mask:0xf bound_ctrl:1
	v_add_f32_dpp v152, v152, v152 row_ror:2 row_mask:0xf bank_mask:0xf bound_ctrl:1
	v_add_f32_dpp v153, v153, v153 row_ror:2 row_mask:0xf bank_mask:0xf bound_ctrl:1
	v_add_f32_dpp v154, v154, v154 row_ror:2 row_mask:0xf bank_mask:0xf bound_ctrl:1
	v_mov_b32_dpp v155, v151 row_ror:1 row_mask:0xf bank_mask:0xf bound_ctrl:1
	v_mov_b32_dpp v156, v152 row_ror:1 row_mask:0xf bank_mask:0xf bound_ctrl:1
	v_mov_b32_dpp v157, v153 row_ror:1 row_mask:0xf bank_mask:0xf bound_ctrl:1
	v_mov_b32_dpp v158, v154 row_ror:1 row_mask:0xf bank_mask:0xf bound_ctrl:1
	v_add_u32_e32 v142, 0x2000, v137
	s_mov_b64 exec, s[0:1]
	v_add_f32_e32 v151, v151, v155
	v_add_f32_e32 v152, v152, v156
	v_add_f32_e32 v153, v153, v157
	v_add_f32_e32 v154, v154, v158
	global_store_dword v142, v151, s[2:3] offset:3072
	global_store_dword v142, v152, s[2:3] offset:3136
	global_store_dword v142, v153, s[2:3] offset:3200
	global_store_dword v142, v154, s[2:3] offset:3264
	s_mov_b64 exec, -1
	s_mov_b64 s[0:1], exec
	s_branch .LBB0_444
